# attention tile loop software-pipelined: QK(i+1) MFMAs overlap softmax(i) VALU, PV(i) overlaps rowmax(i+1); unrolled x2, static LDS offsets
# speedup vs baseline: 1.0755x; 1.0312x over previous
; #define LAS __attribute__((address_space(3)))
; #define LGK(n, f) asm volatile("s_waitcnt lgkmcnt(%1)" : "+v"(f) : "n"(n))
; __device__ __forceinline__ void attn_phase(int wv, const bf16_t* Q, const bf16_t* Kf, const bf16_t* Vt, const bf16_t* proj, bf16_t* mixed, LAS unsigned char* lds) { LIDS
;     ...
;             const int qb = half == 0 ? 63 - pi : pi;
;             const int q0 = qb * 256, qw0 = q0 + 32 * wid, q = qw0 + r, nt = 4 * qb + 4;
;             const char* kbase = (const char*)Kf + head * 192 * 2; const char* vbase = (const char*)Vt + (size_t)head * 128 * SEQ * 2;
;             bf16x8 qf[12];
; #pragma unroll
;             for (int ks = 0; ks < 12; ++ks) qf[ks] = *(const bf16x8*)(Q + (size_t)q * NQ + head * 192 + ks * 16 + h * 8);
;             float zf = 0.f; asm volatile("" : "+v"(zf));
;             f32x16 o[4];
; #pragma unroll
;             for (int b = 0; b < 4; ++b)
; #pragma unroll
;                 for (int j = 0; j < 16; ++j) o[b][j] = zf;
;             float mrun = -1e30f, lsum = 0.f;
;             asm volatile("" ::: "memory"); __builtin_amdgcn_s_barrier(); asm volatile("" ::: "memory");
;             ATT_ISSUE(0, 0);
;             for (int t = 0; t < nt; ++t) {
;                 const int b = t & 1;
;                 asm volatile("s_waitcnt vmcnt(0)" ::: "memory"); __builtin_amdgcn_s_barrier(); asm volatile("" ::: "memory");
;                 if (t + 1 < nt) ATT_ISSUE(t + 1, b ^ 1);
;                 if (64 * t <= qw0 + 31) {
;                     LAS unsigned char* kb_ = lds + b * ATT_STAGE; LAS unsigned char* vb_ = kb_ + ATT_KB;
;                     f32x16 s[2];
; #pragma unroll
;                     for (int kb = 0; kb < 2; ++kb)
; #pragma unroll
;                         for (int j = 0; j < 16; ++j) s[kb][j] = zf;
;                     unsigned kad[4];
; #pragma unroll
;                     for (int kl = 0; kl < 4; ++kl) kad[kl] = (unsigned)(size_t)kb_ + (unsigned)koffl[kl];
;                     bf16x8 fr_[4];
;     ...
;                     ATT_KRD(0); ATT_KRD(1); ATT_KRD(2); ATT_KRD(3);
; #pragma unroll
;                     for (int i = 0; i < 24; ++i) {
;                         LGK(i < 21 ? 3 : 23 - i, fr_[i & 3]);
;                         s[i & 1] = __builtin_amdgcn_mfma_f32_32x32x16_bf16(fr_[i & 3], qf[i >> 1], s[i & 1], 0, 0, 0);
;                         if (i + 4 < 24) ATT_KRD(i + 4);
;                     }
.LBB0_98:
	s_and_b64 s[16:17], s[68:69], exec
	s_cselect_b32 s17, s78, s59
	s_lshl_b32 s16, s17, 8
	s_add_i32 s16, s16, s56
	v_or_b32_e32 v223, s16, v206
	v_mad_i64_i32 v[0:1], s[18:19], v223, s27, v[204:205]
	global_load_dwordx4 v[112:115], v[0:1], off
	global_load_dwordx4 v[116:119], v[0:1], off offset:32
	global_load_dwordx4 v[120:123], v[0:1], off offset:64
	global_load_dwordx4 v[124:127], v[0:1], off offset:96
	global_load_dwordx4 v[128:131], v[0:1], off offset:128
	global_load_dwordx4 v[132:135], v[0:1], off offset:160
	global_load_dwordx4 v[136:139], v[0:1], off offset:192
	global_load_dwordx4 v[140:143], v[0:1], off offset:224
	global_load_dwordx4 v[144:147], v[0:1], off offset:256
	global_load_dwordx4 v[148:151], v[0:1], off offset:288
	global_load_dwordx4 v[152:155], v[0:1], off offset:320
	global_load_dwordx4 v[156:159], v[0:1], off offset:352
	v_mov_b32_e32 v0, v177
	s_mov_b64 s[18:19], s[6:7]
	s_mov_b64 s[20:21], s[4:5]
	s_mov_b32 m0, s58
	s_barrier
	v_mov_b32_e32 v1, v0
	v_lshl_add_u64 v[2:3], s[20:21], 0, v[176:177]
	global_load_lds_dwordx4 v[2:3], off
	v_lshl_add_u64 v[2:3], s[20:21], 0, v[194:195]
	s_add_i32 m0, s58, 0x2000
	v_mov_b32_e32 v4, v0
	global_load_lds_dwordx4 v[2:3], off
	v_lshl_add_u64 v[2:3], s[20:21], 0, v[196:197]
	s_add_i32 m0, s58, 0x4000
	v_mov_b32_e32 v5, v0
	global_load_lds_dwordx4 v[2:3], off
	v_lshl_add_u64 v[2:3], s[18:19], 0, v[198:199]
	s_add_i32 m0, s58, 0x6000
	v_mov_b32_e32 v6, v0
	global_load_lds_dwordx4 v[2:3], off
	v_lshl_add_u64 v[2:3], s[18:19], 0, v[200:201]
	s_add_i32 m0, s58, 0x8000
	v_mov_b32_e32 v7, v0
	global_load_lds_dwordx4 v[2:3], off
	v_mov_b32_e32 v2, v0
	v_mov_b32_e32 v3, v0
	v_mov_b32_e32 v8, v0
	v_mov_b32_e32 v9, v0
	v_mov_b32_e32 v10, v0
	v_mov_b32_e32 v11, v0
	v_mov_b32_e32 v12, v0
	v_mov_b32_e32 v13, v0
	v_mov_b32_e32 v14, v0
	s_cmp_lt_i32 s17, 0
	v_mov_b32_e32 v15, v0
	s_cbranch_scc1 .LBB0_109
	s_lshl_b32 s17, s17, 2
	v_mov_b64_e32 v[62:63], v[14:15]
	v_mov_b64_e32 v[46:47], v[14:15]
	v_mov_b64_e32 v[30:31], v[14:15]
	v_mov_b64_e32 v[78:79], v[14:15]
	s_add_i32 s17, s17, 4
	s_or_b32 s18, s16, 31
	s_mov_b32 s19, 0
	v_mov_b32_e32 v224, 0
	v_mov_b32_e32 v225, 0xf149f2ca
	s_mov_b32 s20, 63
	s_mov_b64 s[62:63], s[12:13]
	s_mov_b64 s[72:73], s[10:11]
	v_mov_b64_e32 v[60:61], v[12:13]
	v_mov_b64_e32 v[58:59], v[10:11]
	v_mov_b64_e32 v[56:57], v[8:9]
	v_mov_b64_e32 v[54:55], v[6:7]
	v_mov_b64_e32 v[52:53], v[4:5]
	v_mov_b64_e32 v[50:51], v[2:3]
	v_mov_b64_e32 v[48:49], v[0:1]
	v_mov_b64_e32 v[44:45], v[12:13]
	v_mov_b64_e32 v[42:43], v[10:11]
	v_mov_b64_e32 v[40:41], v[8:9]
	v_mov_b64_e32 v[38:39], v[6:7]
	v_mov_b64_e32 v[36:37], v[4:5]
	v_mov_b64_e32 v[34:35], v[2:3]
	v_mov_b64_e32 v[32:33], v[0:1]
	v_mov_b64_e32 v[28:29], v[12:13]
	v_mov_b64_e32 v[26:27], v[10:11]
	v_mov_b64_e32 v[24:25], v[8:9]
	v_mov_b64_e32 v[22:23], v[6:7]
	v_mov_b64_e32 v[20:21], v[4:5]
	v_mov_b64_e32 v[18:19], v[2:3]
	v_mov_b64_e32 v[16:17], v[0:1]
	v_mov_b64_e32 v[76:77], v[12:13]
	v_mov_b64_e32 v[74:75], v[10:11]
	v_mov_b64_e32 v[72:73], v[8:9]
	v_mov_b64_e32 v[70:71], v[6:7]
	v_mov_b64_e32 v[68:69], v[4:5]
	v_mov_b64_e32 v[66:67], v[2:3]
	v_mov_b64_e32 v[64:65], v[0:1]
	v_mov_b32_e32 v247, v215
	v_add_u32_e32 v210, 0x8000, v218
	v_add_u32_e32 v211, 0x8000, v219
	v_add_u32_e32 v212, 0x8000, v220
	v_add_u32_e32 v213, 0x8000, v221
	s_lshr_b32 s21, s16, 6
	s_add_i32 m0, s58, 0xa000
	s_nop 0
	global_load_lds_dwordx4 v176, s[62:63]
	s_add_i32 m0, s58, 0xc000
	s_nop 0
	global_load_lds_dwordx4 v194, s[62:63]
	s_add_i32 m0, s58, 0xe000
	s_nop 0
	global_load_lds_dwordx4 v196, s[62:63]
	s_add_u32 s62, s62, 0x30000
	s_addc_u32 s63, s63, 0
	s_waitcnt vmcnt(0)
	s_barrier
	ds_read_b128 v[160:163], v207 offset:0x10
	ds_read_b128 v[164:167], v207 offset:0x3010
	ds_read_b128 v[168:171], v208 offset:0x10
	ds_read_b128 v[172:175], v208 offset:0x3010
	s_waitcnt lgkmcnt(3)
	v_mfma_f32_32x32x16_bf16 v[96:111], v[160:163], v[112:115], v[0:15]
	ds_read_b128 v[160:163], v209 offset:0x10
	s_waitcnt lgkmcnt(3)
	v_mfma_f32_32x32x16_bf16 v[80:95], v[164:167], v[112:115], v[0:15]
	ds_read_b128 v[164:167], v209 offset:0x3010
	s_waitcnt lgkmcnt(3)
	v_mfma_f32_32x32x16_bf16 v[96:111], v[168:171], v[116:119], v[96:111]
	ds_read_b128 v[168:171], v217 offset:0x10
	s_waitcnt lgkmcnt(3)
	v_mfma_f32_32x32x16_bf16 v[80:95], v[172:175], v[116:119], v[80:95]
	ds_read_b128 v[172:175], v217 offset:0x3010
	s_waitcnt lgkmcnt(3)
	v_mfma_f32_32x32x16_bf16 v[96:111], v[160:163], v[120:123], v[96:111]
	ds_read_b128 v[160:163], v207 offset:0x90
	s_waitcnt lgkmcnt(3)
	v_mfma_f32_32x32x16_bf16 v[80:95], v[164:167], v[120:123], v[80:95]
	ds_read_b128 v[164:167], v207 offset:0x3090
	s_waitcnt lgkmcnt(3)
	v_mfma_f32_32x32x16_bf16 v[96:111], v[168:171], v[124:127], v[96:111]
	ds_read_b128 v[168:171], v208 offset:0x90
	s_waitcnt lgkmcnt(3)
	v_mfma_f32_32x32x16_bf16 v[80:95], v[172:175], v[124:127], v[80:95]
	ds_read_b128 v[172:175], v208 offset:0x3090
	s_waitcnt lgkmcnt(3)
	v_mfma_f32_32x32x16_bf16 v[96:111], v[160:163], v[128:131], v[96:111]
	ds_read_b128 v[160:163], v209 offset:0x90
	s_waitcnt lgkmcnt(3)
	v_mfma_f32_32x32x16_bf16 v[80:95], v[164:167], v[128:131], v[80:95]
	ds_read_b128 v[164:167], v209 offset:0x3090
	s_waitcnt lgkmcnt(3)
	v_mfma_f32_32x32x16_bf16 v[96:111], v[168:171], v[132:135], v[96:111]
	ds_read_b128 v[168:171], v217 offset:0x90
	s_waitcnt lgkmcnt(3)
	v_mfma_f32_32x32x16_bf16 v[80:95], v[172:175], v[132:135], v[80:95]
	ds_read_b128 v[172:175], v217 offset:0x3090
	s_waitcnt lgkmcnt(3)
	v_mfma_f32_32x32x16_bf16 v[96:111], v[160:163], v[136:139], v[96:111]
	ds_read_b128 v[160:163], v207 offset:0x110
	s_waitcnt lgkmcnt(3)
	v_mfma_f32_32x32x16_bf16 v[80:95], v[164:167], v[136:139], v[80:95]
	ds_read_b128 v[164:167], v207 offset:0x3110
	s_waitcnt lgkmcnt(3)
	v_mfma_f32_32x32x16_bf16 v[96:111], v[168:171], v[140:143], v[96:111]
	ds_read_b128 v[168:171], v208 offset:0x110
	s_waitcnt lgkmcnt(3)
	v_mfma_f32_32x32x16_bf16 v[80:95], v[172:175], v[140:143], v[80:95]
	ds_read_b128 v[172:175], v208 offset:0x3110
	s_waitcnt lgkmcnt(3)
	v_mfma_f32_32x32x16_bf16 v[96:111], v[160:163], v[144:147], v[96:111]
	ds_read_b128 v[160:163], v209 offset:0x110
	s_waitcnt lgkmcnt(3)
	v_mfma_f32_32x32x16_bf16 v[80:95], v[164:167], v[144:147], v[80:95]
	ds_read_b128 v[164:167], v209 offset:0x3110
	s_waitcnt lgkmcnt(3)
	v_mfma_f32_32x32x16_bf16 v[96:111], v[168:171], v[148:151], v[96:111]
	ds_read_b128 v[168:171], v217 offset:0x110
	s_waitcnt lgkmcnt(3)
	v_mfma_f32_32x32x16_bf16 v[80:95], v[172:175], v[148:151], v[80:95]
	ds_read_b128 v[172:175], v217 offset:0x3110
	s_waitcnt lgkmcnt(3)
	v_mfma_f32_32x32x16_bf16 v[96:111], v[160:163], v[152:155], v[96:111]
	s_waitcnt lgkmcnt(2)
	v_mfma_f32_32x32x16_bf16 v[80:95], v[164:167], v[152:155], v[80:95]
	s_waitcnt lgkmcnt(1)
	v_mfma_f32_32x32x16_bf16 v[96:111], v[168:171], v[156:159], v[96:111]
	s_waitcnt lgkmcnt(0)
	v_mfma_f32_32x32x16_bf16 v[80:95], v[172:175], v[156:159], v[80:95]
	s_cmp_lg_u32 s21, 0
	s_cbranch_scc1 .Lp2_nomask1
; __device__ __forceinline__ unsigned cvt_pk_bf16(float lo, float hi) { unsigned r; asm volatile("v_cvt_pk_bf16_f32 %0, %1, %2" : "=v"(r) : "v"(lo), "v"(hi)); return r; }
; __device__ __forceinline__ float fast_exp2(float x) { return __builtin_amdgcn_exp2f(x); }
; __device__ __forceinline__ void attn_phase(int wv, const bf16_t* Q, const bf16_t* Kf, const bf16_t* Vt, const bf16_t* proj, bf16_t* mixed, LAS unsigned char* lds) { LIDS
;     ...
;                     if (64 * t + 63 > qw0) {
; #pragma unroll
;                         for (int kb = 0; kb < 2; ++kb)
; #pragma unroll
;                             for (int j = 0; j < 16; ++j) { const int key = 64 * t + 32 * kb + 16 * (j >> 3) + 8 * h + (j & 7); if (key > q) s[kb][j] = -1e30f; }
;                     }
;                     float mx = -1e30f;
; #pragma unroll
;                     for (int kb = 0; kb < 2; ++kb)
; #pragma unroll
;                         for (int j = 0; j < 16; ++j) mx = fmaxf(mx, s[kb][j]);
;                     mx = fmaxf(mx, __shfl_xor(mx, 32));
;                     if (__builtin_amdgcn_ballot_w64(mx > mrun + 8.0f) != 0ull) {
;                         const float mnew = fmaxf(mrun, mx), alpha = fast_exp2(mrun - mnew); mrun = mnew;
;                         lsum *= alpha;
; #pragma unroll
;                         for (int bb = 0; bb < 4; ++bb)
; #pragma unroll
;                             for (int j = 0; j < 16; ++j) o[bb][j] *= alpha;
;                     }
;                     float ps = 0.f;
; #pragma unroll
;                     for (int kb = 0; kb < 2; ++kb)
; #pragma unroll
;                         for (int j = 0; j < 16; ++j) { s[kb][j] = fast_exp2(s[kb][j] - mrun); ps += s[kb][j]; }
;                     lsum += ps;
; #pragma unroll
;                     for (int c = 0; c < 4; ++c) {
;                         const int kb = c >> 1, sx = c & 1;
;                         u32x4 pw;
; #pragma unroll
;                         for (int j = 0; j < 4; ++j) pw[j] = cvt_pk_bf16(s[kb][8 * sx + 2 * j], s[kb][8 * sx + 2 * j + 1]);
	s_mov_b32 s23, 0
	s_nop 12
	v_add_u32_e32 v244, s23, v222
	v_sub_u32_e32 v244, v223, v244
	v_cmp_le_i32_e32 vcc, 0, v244
	s_nop 1
	v_cndmask_b32_e32 v96, v215, v96, vcc
	v_cmp_le_i32_e32 vcc, 1, v244
	s_nop 1
	v_cndmask_b32_e32 v97, v215, v97, vcc
	v_cmp_le_i32_e32 vcc, 2, v244
	s_nop 1
	v_cndmask_b32_e32 v98, v215, v98, vcc
	v_cmp_le_i32_e32 vcc, 3, v244
	s_nop 1
	v_cndmask_b32_e32 v99, v215, v99, vcc
	v_cmp_le_i32_e32 vcc, 4, v244
	s_nop 1
	v_cndmask_b32_e32 v100, v215, v100, vcc
	v_cmp_le_i32_e32 vcc, 5, v244
	s_nop 1
	v_cndmask_b32_e32 v101, v215, v101, vcc
	v_cmp_le_i32_e32 vcc, 6, v244
	s_nop 1
	v_cndmask_b32_e32 v102, v215, v102, vcc
	v_cmp_le_i32_e32 vcc, 7, v244
	s_nop 1
	v_cndmask_b32_e32 v103, v215, v103, vcc
	v_cmp_le_i32_e32 vcc, 16, v244
	s_nop 1
	v_cndmask_b32_e32 v104, v215, v104, vcc
	v_cmp_le_i32_e32 vcc, 17, v244
	s_nop 1
	v_cndmask_b32_e32 v105, v215, v105, vcc
	v_cmp_le_i32_e32 vcc, 18, v244
	s_nop 1
	v_cndmask_b32_e32 v106, v215, v106, vcc
	v_cmp_le_i32_e32 vcc, 19, v244
	s_nop 1
	v_cndmask_b32_e32 v107, v215, v107, vcc
	v_cmp_le_i32_e32 vcc, 20, v244
	s_nop 1
	v_cndmask_b32_e32 v108, v215, v108, vcc
	v_cmp_le_i32_e32 vcc, 21, v244
	s_nop 1
	v_cndmask_b32_e32 v109, v215, v109, vcc
	v_cmp_le_i32_e32 vcc, 22, v244
	s_nop 1
	v_cndmask_b32_e32 v110, v215, v110, vcc
	v_cmp_le_i32_e32 vcc, 23, v244
	s_nop 1
	v_cndmask_b32_e32 v111, v215, v111, vcc
	v_cmp_le_i32_e32 vcc, 32, v244
	s_nop 1
	v_cndmask_b32_e32 v80, v215, v80, vcc
	v_cmp_le_i32_e32 vcc, 33, v244
	s_nop 1
	v_cndmask_b32_e32 v81, v215, v81, vcc
	v_cmp_le_i32_e32 vcc, 34, v244
	s_nop 1
	v_cndmask_b32_e32 v82, v215, v82, vcc
	v_cmp_le_i32_e32 vcc, 35, v244
	s_nop 1
	v_cndmask_b32_e32 v83, v215, v83, vcc
	v_cmp_le_i32_e32 vcc, 36, v244
	s_nop 1
	v_cndmask_b32_e32 v84, v215, v84, vcc
	v_cmp_le_i32_e32 vcc, 37, v244
	s_nop 1
	v_cndmask_b32_e32 v85, v215, v85, vcc
	v_cmp_le_i32_e32 vcc, 38, v244
	s_nop 1
	v_cndmask_b32_e32 v86, v215, v86, vcc
	v_cmp_le_i32_e32 vcc, 39, v244
	s_nop 1
	v_cndmask_b32_e32 v87, v215, v87, vcc
	v_cmp_le_i32_e32 vcc, 48, v244
	s_nop 1
	v_cndmask_b32_e32 v88, v215, v88, vcc
	v_cmp_le_i32_e32 vcc, 49, v244
	s_nop 1
	v_cndmask_b32_e32 v89, v215, v89, vcc
	v_cmp_le_i32_e32 vcc, 50, v244
	s_nop 1
	v_cndmask_b32_e32 v90, v215, v90, vcc
	v_cmp_le_i32_e32 vcc, 51, v244
	s_nop 1
	v_cndmask_b32_e32 v91, v215, v91, vcc
	v_cmp_le_i32_e32 vcc, 52, v244
	s_nop 1
	v_cndmask_b32_e32 v92, v215, v92, vcc
	v_cmp_le_i32_e32 vcc, 53, v244
	s_nop 1
	v_cndmask_b32_e32 v93, v215, v93, vcc
	v_cmp_le_i32_e32 vcc, 54, v244
	s_nop 1
	v_cndmask_b32_e32 v94, v215, v94, vcc
	v_cmp_le_i32_e32 vcc, 55, v244
	s_nop 1
	v_cndmask_b32_e32 v95, v215, v95, vcc
.Lp2_nomask1:
	s_nop 12
	v_max3_f32 v226, v96, v97, v98
	v_max3_f32 v226, v226, v99, v100
	v_max3_f32 v226, v226, v101, v102
	v_max3_f32 v226, v226, v103, v104
	v_max3_f32 v226, v226, v105, v106
	v_max3_f32 v226, v226, v107, v108
	v_max3_f32 v226, v226, v109, v110
	v_max_f32_e32 v226, v226, v111
	v_max3_f32 v227, v80, v81, v82
	v_max3_f32 v227, v227, v83, v84
	v_max3_f32 v227, v227, v85, v86
	v_max3_f32 v227, v227, v87, v88
	v_max3_f32 v227, v227, v89, v90
	v_max3_f32 v227, v227, v91, v92
	v_max3_f32 v227, v227, v93, v94
	v_max_f32_e32 v227, v227, v95
	v_max_f32_e32 v226, v226, v227
	v_mov_b32_e32 v227, v226
	s_nop 1
	v_permlane32_swap_b32_e32 v226, v227
	v_max_f32_e32 v226, v226, v227
	v_cmp_gt_f32_e32 vcc, v226, v247
	s_cbranch_vccnz .Lp2_rareP
.Lp2_loop0:
.Lp2_top0:
	s_waitcnt vmcnt(0)
	s_barrier
	s_add_i32 s22, s19, 2
	s_add_i32 s24, s19, 1
	s_cmp_gt_i32 s19, s21
	s_cbranch_scc1 .Lp2_idle0
	s_cmp_eq_u32 s19, s21
	s_cbranch_scc1 .Lp2_drain0
	ds_read_b128 v[160:163], v207 offset:0xa010
	ds_read_b128 v[164:167], v207 offset:0xd010
	ds_read_b128 v[168:171], v208 offset:0xa010
	ds_read_b128 v[172:175], v208 offset:0xd010
	s_waitcnt lgkmcnt(3)
	v_mfma_f32_32x32x16_bf16 v[228:243], v[160:163], v[112:115], v[0:15]
	ds_read_b128 v[160:163], v209 offset:0xa010
	v_exp_f32_e32 v96, v96
	v_exp_f32_e32 v97, v97
	s_nop 0
	v_add_f32_e32 v246, v96, v97
	s_waitcnt lgkmcnt(3)
	v_mfma_f32_32x32x16_bf16 v[178:193], v[164:167], v[112:115], v[0:15]
	ds_read_b128 v[164:167], v209 offset:0xd010
	v_cvt_pk_bf16_f32 v96, v96, v97
	v_exp_f32_e32 v98, v98
	v_exp_f32_e32 v99, v99
	s_cmp_ge_i32 s22, s17
	s_cbranch_scc1 .Lp2_nd2
	s_mov_b32 m0, s58
	s_nop 0
	global_load_lds_dwordx4 v176, s[62:63]
.Lp2_nd2:
	s_waitcnt lgkmcnt(3)
	v_mfma_f32_32x32x16_bf16 v[228:243], v[168:171], v[116:119], v[228:243]
	ds_read_b128 v[168:171], v217 offset:0xa010
	v_add_f32_e32 v246, v246, v98
	v_add_f32_e32 v246, v246, v99
	v_cvt_pk_bf16_f32 v97, v98, v99
	v_exp_f32_e32 v100, v100
	s_waitcnt lgkmcnt(3)
	v_mfma_f32_32x32x16_bf16 v[178:193], v[172:175], v[116:119], v[178:193]
	ds_read_b128 v[172:175], v217 offset:0xd010
	v_exp_f32_e32 v101, v101
	v_add_f32_e32 v246, v246, v100
	v_add_f32_e32 v246, v246, v101
	v_cvt_pk_bf16_f32 v98, v100, v101
	s_waitcnt lgkmcnt(3)
	v_mfma_f32_32x32x16_bf16 v[228:243], v[160:163], v[120:123], v[228:243]
	ds_read_b128 v[160:163], v207 offset:0xa090
	v_exp_f32_e32 v102, v102
	v_exp_f32_e32 v103, v103
	v_add_f32_e32 v246, v246, v102
	s_waitcnt lgkmcnt(3)
	v_mfma_f32_32x32x16_bf16 v[178:193], v[164:167], v[120:123], v[178:193]
	ds_read_b128 v[164:167], v207 offset:0xd090
	v_add_f32_e32 v246, v246, v103
	v_cvt_pk_bf16_f32 v99, v102, v103
	v_exp_f32_e32 v104, v104
	s_cmp_ge_i32 s22, s17
	s_cbranch_scc1 .Lp2_nd3
	s_add_i32 m0, s58, 0x2000
	s_nop 0
	global_load_lds_dwordx4 v194, s[62:63]
; __device__ __forceinline__ float fast_exp2(float x) { return __builtin_amdgcn_exp2f(x); }
; __device__ __forceinline__ void attn_phase(int wv, const bf16_t* Q, const bf16_t* Kf, const bf16_t* Vt, const bf16_t* proj, bf16_t* mixed, LAS unsigned char* lds) { LIDS
;     ...
;                     ATT_KRD(0); ATT_KRD(1); ATT_KRD(2); ATT_KRD(3);
; #pragma unroll
;                     for (int i = 0; i < 24; ++i) {
;                         LGK(i < 21 ? 3 : 23 - i, fr_[i & 3]);
;                         s[i & 1] = __builtin_amdgcn_mfma_f32_32x32x16_bf16(fr_[i & 3], qf[i >> 1], s[i & 1], 0, 0, 0);
;                         if (i + 4 < 24) ATT_KRD(i + 4);
;                     }
;     ...
;                     unsigned vad[4];
; #pragma unroll
;                     for (int c = 0; c < 4; ++c) vad[c] = (unsigned)(size_t)vb_ + (unsigned)voffl[c];
;     ...
;                     ATT_VRD(0); ATT_VRD(1); ATT_VRD(2); ATT_VRD(3);
;                     if (64 * t + 63 > qw0) {
; #pragma unroll
;                         for (int kb = 0; kb < 2; ++kb)
; #pragma unroll
;                             for (int j = 0; j < 16; ++j) { const int key = 64 * t + 32 * kb + 16 * (j >> 3) + 8 * h + (j & 7); if (key > q) s[kb][j] = -1e30f; }
;                     }
;                     float mx = -1e30f;
; #pragma unroll
;                     for (int kb = 0; kb < 2; ++kb)
; #pragma unroll
;                         for (int j = 0; j < 16; ++j) mx = fmaxf(mx, s[kb][j]);
;                     mx = fmaxf(mx, __shfl_xor(mx, 32));
;                     if (__builtin_amdgcn_ballot_w64(mx > mrun + 8.0f) != 0ull) {
;                         const float mnew = fmaxf(mrun, mx), alpha = fast_exp2(mrun - mnew); mrun = mnew;
;                         lsum *= alpha;
; #pragma unroll
;                         for (int bb = 0; bb < 4; ++bb)
; #pragma unroll
;                             for (int j = 0; j < 16; ++j) o[bb][j] *= alpha;
;                     }
;                     float ps = 0.f;
; #pragma unroll
;                     for (int kb = 0; kb < 2; ++kb)
; #pragma unroll
;                         for (int j = 0; j < 16; ++j) { s[kb][j] = fast_exp2(s[kb][j] - mrun); ps += s[kb][j]; }
;                     lsum += ps;
; #pragma unroll
;                     for (int c = 0; c < 4; ++c) {
;                         const int kb = c >> 1, sx = c & 1;
;                         u32x4 pw;
; #pragma unroll
.Lp2_nd3:
	s_waitcnt lgkmcnt(3)
	v_mfma_f32_32x32x16_bf16 v[228:243], v[168:171], v[124:127], v[228:243]
	ds_read_b128 v[168:171], v208 offset:0xa090
	v_exp_f32_e32 v105, v105
	v_add_f32_e32 v246, v246, v104
	v_add_f32_e32 v246, v246, v105
	v_cvt_pk_bf16_f32 v100, v104, v105
	s_waitcnt lgkmcnt(3)
	v_mfma_f32_32x32x16_bf16 v[178:193], v[172:175], v[124:127], v[178:193]
	ds_read_b128 v[172:175], v208 offset:0xd090
	v_exp_f32_e32 v106, v106
	v_exp_f32_e32 v107, v107
	v_add_f32_e32 v246, v246, v106
	s_waitcnt lgkmcnt(3)
	v_mfma_f32_32x32x16_bf16 v[228:243], v[160:163], v[128:131], v[228:243]
	ds_read_b128 v[160:163], v209 offset:0xa090
	v_add_f32_e32 v246, v246, v107
	v_cvt_pk_bf16_f32 v101, v106, v107
	v_exp_f32_e32 v108, v108
	s_waitcnt lgkmcnt(3)
	v_mfma_f32_32x32x16_bf16 v[178:193], v[164:167], v[128:131], v[178:193]
	ds_read_b128 v[164:167], v209 offset:0xd090
	v_exp_f32_e32 v109, v109
	v_add_f32_e32 v246, v246, v108
	v_add_f32_e32 v246, v246, v109
	v_cvt_pk_bf16_f32 v102, v108, v109
	s_cmp_ge_i32 s22, s17
	s_cbranch_scc1 .Lp2_nd4
	s_add_i32 m0, s58, 0x4000
	s_nop 0
	global_load_lds_dwordx4 v196, s[62:63]
.Lp2_nd4:
	s_waitcnt lgkmcnt(3)
	v_mfma_f32_32x32x16_bf16 v[228:243], v[168:171], v[132:135], v[228:243]
	ds_read_b128 v[168:171], v217 offset:0xa090
	v_exp_f32_e32 v110, v110
	v_exp_f32_e32 v111, v111
	v_add_f32_e32 v246, v246, v110
	s_waitcnt lgkmcnt(3)
	v_mfma_f32_32x32x16_bf16 v[178:193], v[172:175], v[132:135], v[178:193]
	ds_read_b128 v[172:175], v217 offset:0xd090
	v_add_f32_e32 v246, v246, v111
	v_cvt_pk_bf16_f32 v103, v110, v111
	v_exp_f32_e32 v80, v80
	s_waitcnt lgkmcnt(3)
	v_mfma_f32_32x32x16_bf16 v[228:243], v[160:163], v[136:139], v[228:243]
	ds_read_b128 v[160:163], v207 offset:0xa110
	v_exp_f32_e32 v81, v81
	v_add_f32_e32 v246, v246, v80
	v_add_f32_e32 v246, v246, v81
	v_cvt_pk_bf16_f32 v80, v80, v81
	s_waitcnt lgkmcnt(3)
	v_mfma_f32_32x32x16_bf16 v[178:193], v[164:167], v[136:139], v[178:193]
	ds_read_b128 v[164:167], v207 offset:0xd110
	v_exp_f32_e32 v82, v82
	v_exp_f32_e32 v83, v83
	v_add_f32_e32 v246, v246, v82
	s_cmp_ge_i32 s24, s17
	s_cbranch_scc1 .Lp2_nd5
	s_add_i32 m0, s58, 0x10000
	s_nop 0
	global_load_lds_dwordx4 v198, s[72:73]
.Lp2_nd5:
	s_waitcnt lgkmcnt(3)
	v_mfma_f32_32x32x16_bf16 v[228:243], v[168:171], v[140:143], v[228:243]
	ds_read_b128 v[168:171], v208 offset:0xa110
	v_add_f32_e32 v246, v246, v83
	v_cvt_pk_bf16_f32 v81, v82, v83
	v_exp_f32_e32 v84, v84
	s_waitcnt lgkmcnt(3)
	v_mfma_f32_32x32x16_bf16 v[178:193], v[172:175], v[140:143], v[178:193]
	ds_read_b128 v[172:175], v208 offset:0xd110
	v_exp_f32_e32 v85, v85
	v_add_f32_e32 v246, v246, v84
	v_add_f32_e32 v246, v246, v85
	v_cvt_pk_bf16_f32 v82, v84, v85
	s_waitcnt lgkmcnt(3)
	v_mfma_f32_32x32x16_bf16 v[228:243], v[160:163], v[144:147], v[228:243]
	ds_read_b128 v[160:163], v209 offset:0xa110
	v_exp_f32_e32 v86, v86
	v_exp_f32_e32 v87, v87
	v_add_f32_e32 v246, v246, v86
	s_waitcnt lgkmcnt(3)
	v_mfma_f32_32x32x16_bf16 v[178:193], v[164:167], v[144:147], v[178:193]
	ds_read_b128 v[164:167], v209 offset:0xd110
	v_add_f32_e32 v246, v246, v87
	v_cvt_pk_bf16_f32 v83, v86, v87
	v_exp_f32_e32 v88, v88
	s_cmp_ge_i32 s24, s17
	s_cbranch_scc1 .Lp2_nd6
	s_add_i32 m0, s58, 0x12000
	s_nop 0
	global_load_lds_dwordx4 v200, s[72:73]
.Lp2_nd6:
	s_waitcnt lgkmcnt(3)
	v_mfma_f32_32x32x16_bf16 v[228:243], v[168:171], v[148:151], v[228:243]
	ds_read_b128 v[168:171], v217 offset:0xa110
	v_exp_f32_e32 v89, v89
	v_add_f32_e32 v246, v246, v88
	v_add_f32_e32 v246, v246, v89
	v_cvt_pk_bf16_f32 v84, v88, v89
	s_waitcnt lgkmcnt(3)
	v_mfma_f32_32x32x16_bf16 v[178:193], v[172:175], v[148:151], v[178:193]
	ds_read_b128 v[172:175], v217 offset:0xd110
	v_exp_f32_e32 v90, v90
	v_exp_f32_e32 v91, v91
	v_add_f32_e32 v246, v246, v90
	s_waitcnt lgkmcnt(3)
	v_mfma_f32_32x32x16_bf16 v[228:243], v[160:163], v[152:155], v[228:243]
	ds_read_b128 v[160:163], v218 offset:0x6010
	v_add_f32_e32 v246, v246, v91
	v_cvt_pk_bf16_f32 v85, v90, v91
	v_exp_f32_e32 v92, v92
	s_waitcnt lgkmcnt(3)
	v_mfma_f32_32x32x16_bf16 v[178:193], v[164:167], v[152:155], v[178:193]
	ds_read_b128 v[164:167], v218 offset:0x7010
	v_exp_f32_e32 v93, v93
	v_add_f32_e32 v246, v246, v92
	v_add_f32_e32 v246, v246, v93
	v_cvt_pk_bf16_f32 v86, v92, v93
	s_waitcnt lgkmcnt(3)
	v_mfma_f32_32x32x16_bf16 v[228:243], v[168:171], v[156:159], v[228:243]
	ds_read_b128 v[168:171], v218 offset:0x8010
	v_exp_f32_e32 v94, v94
	v_exp_f32_e32 v95, v95
	v_add_f32_e32 v246, v246, v94
	s_waitcnt lgkmcnt(3)
	v_mfma_f32_32x32x16_bf16 v[178:193], v[172:175], v[156:159], v[178:193]
	ds_read_b128 v[172:175], v218 offset:0x9010
	v_add_f32_e32 v246, v246, v95
	v_cvt_pk_bf16_f32 v87, v94, v95
	v_add_f32_e32 v224, v224, v246
	s_waitcnt lgkmcnt(3)
	v_mfma_f32_32x32x16_bf16 v[48:63], v[160:163], v[96:99], v[48:63]
	ds_read_b128 v[160:163], v219 offset:0x6010
	s_waitcnt lgkmcnt(3)
	v_mfma_f32_32x32x16_bf16 v[32:47], v[164:167], v[96:99], v[32:47]
	ds_read_b128 v[164:167], v219 offset:0x7010
	s_waitcnt lgkmcnt(3)
	v_mfma_f32_32x32x16_bf16 v[16:31], v[168:171], v[96:99], v[16:31]
	ds_read_b128 v[168:171], v219 offset:0x8010
	s_waitcnt lgkmcnt(3)
	v_mfma_f32_32x32x16_bf16 v[64:79], v[172:175], v[96:99], v[64:79]
	ds_read_b128 v[172:175], v219 offset:0x9010
	s_cmp_lg_u32 s24, s21
	s_cbranch_scc1 .Lp2_nomask7
; __device__ __forceinline__ float fast_exp2(float x) { return __builtin_amdgcn_exp2f(x); }
; __device__ __forceinline__ void attn_phase(int wv, const bf16_t* Q, const bf16_t* Kf, const bf16_t* Vt, const bf16_t* proj, bf16_t* mixed, LAS unsigned char* lds) { LIDS
;     ...
;                     if (64 * t + 63 > qw0) {
; #pragma unroll
;                         for (int kb = 0; kb < 2; ++kb)
; #pragma unroll
;                             for (int j = 0; j < 16; ++j) { const int key = 64 * t + 32 * kb + 16 * (j >> 3) + 8 * h + (j & 7); if (key > q) s[kb][j] = -1e30f; }
;                     }
;                     float mx = -1e30f;
; #pragma unroll
;                     for (int kb = 0; kb < 2; ++kb)
; #pragma unroll
;                         for (int j = 0; j < 16; ++j) mx = fmaxf(mx, s[kb][j]);
;                     mx = fmaxf(mx, __shfl_xor(mx, 32));
;                     if (__builtin_amdgcn_ballot_w64(mx > mrun + 8.0f) != 0ull) {
;                         const float mnew = fmaxf(mrun, mx), alpha = fast_exp2(mrun - mnew); mrun = mnew;
;                         lsum *= alpha;
; #pragma unroll
;                         for (int bb = 0; bb < 4; ++bb)
; #pragma unroll
;                             for (int j = 0; j < 16; ++j) o[bb][j] *= alpha;
;                     }
;                     float ps = 0.f;
; #pragma unroll
;                     for (int kb = 0; kb < 2; ++kb)
; #pragma unroll
;                         for (int j = 0; j < 16; ++j) { s[kb][j] = fast_exp2(s[kb][j] - mrun); ps += s[kb][j]; }
;                     lsum += ps;
; #pragma unroll
;                     for (int c = 0; c < 4; ++c) {
;                         const int kb = c >> 1, sx = c & 1;
;                         u32x4 pw;
; #pragma unroll
;                         for (int j = 0; j < 4; ++j) pw[j] = cvt_pk_bf16(s[kb][8 * sx + 2 * j], s[kb][8 * sx + 2 * j + 1]);
;                         const bf16x8 pf = __builtin_bit_cast(bf16x8, pw);
; #pragma unroll
;                         for (int bb = 0; bb < 4; ++bb) {
;                             const int j = c * 4 + bb;
;                             LGK(j < 13 ? 3 : 15 - j, fr_[j & 3]);
;                             o[bb] = __builtin_amdgcn_mfma_f32_32x32x16_bf16(fr_[j & 3], pf, o[bb], 0, 0, 0);
;                             if (j + 4 < 16) ATT_VRD(j + 4);
;                         }
;                     }
	s_lshl_b32 s23, s21, 6
	v_add_u32_e32 v244, s23, v222
	v_sub_u32_e32 v244, v223, v244
	v_cmp_le_i32_e32 vcc, 0, v244
	s_nop 1
	v_cndmask_b32_e32 v228, v215, v228, vcc
	v_cmp_le_i32_e32 vcc, 1, v244
	s_nop 1
	v_cndmask_b32_e32 v229, v215, v229, vcc
	v_cmp_le_i32_e32 vcc, 2, v244
	s_nop 1
	v_cndmask_b32_e32 v230, v215, v230, vcc
	v_cmp_le_i32_e32 vcc, 3, v244
	s_nop 1
	v_cndmask_b32_e32 v231, v215, v231, vcc
	v_cmp_le_i32_e32 vcc, 4, v244
	s_nop 1
	v_cndmask_b32_e32 v232, v215, v232, vcc
	v_cmp_le_i32_e32 vcc, 5, v244
	s_nop 1
	v_cndmask_b32_e32 v233, v215, v233, vcc
	v_cmp_le_i32_e32 vcc, 6, v244
	s_nop 1
	v_cndmask_b32_e32 v234, v215, v234, vcc
	v_cmp_le_i32_e32 vcc, 7, v244
	s_nop 1
	v_cndmask_b32_e32 v235, v215, v235, vcc
	v_cmp_le_i32_e32 vcc, 16, v244
	s_nop 1
	v_cndmask_b32_e32 v236, v215, v236, vcc
	v_cmp_le_i32_e32 vcc, 17, v244
	s_nop 1
	v_cndmask_b32_e32 v237, v215, v237, vcc
	v_cmp_le_i32_e32 vcc, 18, v244
	s_nop 1
	v_cndmask_b32_e32 v238, v215, v238, vcc
	v_cmp_le_i32_e32 vcc, 19, v244
	s_nop 1
	v_cndmask_b32_e32 v239, v215, v239, vcc
	v_cmp_le_i32_e32 vcc, 20, v244
	s_nop 1
	v_cndmask_b32_e32 v240, v215, v240, vcc
	v_cmp_le_i32_e32 vcc, 21, v244
	s_nop 1
	v_cndmask_b32_e32 v241, v215, v241, vcc
	v_cmp_le_i32_e32 vcc, 22, v244
	s_nop 1
	v_cndmask_b32_e32 v242, v215, v242, vcc
	v_cmp_le_i32_e32 vcc, 23, v244
	s_nop 1
	v_cndmask_b32_e32 v243, v215, v243, vcc
	v_cmp_le_i32_e32 vcc, 32, v244
	s_nop 1
	v_cndmask_b32_e32 v178, v215, v178, vcc
	v_cmp_le_i32_e32 vcc, 33, v244
	s_nop 1
	v_cndmask_b32_e32 v179, v215, v179, vcc
	v_cmp_le_i32_e32 vcc, 34, v244
	s_nop 1
	v_cndmask_b32_e32 v180, v215, v180, vcc
	v_cmp_le_i32_e32 vcc, 35, v244
	s_nop 1
	v_cndmask_b32_e32 v181, v215, v181, vcc
	v_cmp_le_i32_e32 vcc, 36, v244
	s_nop 1
	v_cndmask_b32_e32 v182, v215, v182, vcc
	v_cmp_le_i32_e32 vcc, 37, v244
	s_nop 1
	v_cndmask_b32_e32 v183, v215, v183, vcc
	v_cmp_le_i32_e32 vcc, 38, v244
	s_nop 1
	v_cndmask_b32_e32 v184, v215, v184, vcc
	v_cmp_le_i32_e32 vcc, 39, v244
	s_nop 1
	v_cndmask_b32_e32 v185, v215, v185, vcc
	v_cmp_le_i32_e32 vcc, 48, v244
	s_nop 1
	v_cndmask_b32_e32 v186, v215, v186, vcc
	v_cmp_le_i32_e32 vcc, 49, v244
	s_nop 1
	v_cndmask_b32_e32 v187, v215, v187, vcc
	v_cmp_le_i32_e32 vcc, 50, v244
	s_nop 1
	v_cndmask_b32_e32 v188, v215, v188, vcc
	v_cmp_le_i32_e32 vcc, 51, v244
	s_nop 1
	v_cndmask_b32_e32 v189, v215, v189, vcc
	v_cmp_le_i32_e32 vcc, 52, v244
	s_nop 1
	v_cndmask_b32_e32 v190, v215, v190, vcc
	v_cmp_le_i32_e32 vcc, 53, v244
	s_nop 1
	v_cndmask_b32_e32 v191, v215, v191, vcc
	v_cmp_le_i32_e32 vcc, 54, v244
	s_nop 1
	v_cndmask_b32_e32 v192, v215, v192, vcc
	v_cmp_le_i32_e32 vcc, 55, v244
	s_nop 1
	v_cndmask_b32_e32 v193, v215, v193, vcc
.Lp2_nomask7:
	s_waitcnt lgkmcnt(3)
	v_mfma_f32_32x32x16_bf16 v[48:63], v[160:163], v[100:103], v[48:63]
	ds_read_b128 v[160:163], v220 offset:0x6010
	v_max3_f32 v226, v228, v229, v230
	v_max3_f32 v226, v226, v231, v232
	s_waitcnt lgkmcnt(3)
	v_mfma_f32_32x32x16_bf16 v[32:47], v[164:167], v[100:103], v[32:47]
	ds_read_b128 v[164:167], v220 offset:0x7010
	v_max3_f32 v226, v226, v233, v234
	v_max3_f32 v226, v226, v235, v236
	s_waitcnt lgkmcnt(3)
	v_mfma_f32_32x32x16_bf16 v[16:31], v[168:171], v[100:103], v[16:31]
	ds_read_b128 v[168:171], v220 offset:0x8010
	v_max3_f32 v226, v226, v237, v238
	v_max3_f32 v226, v226, v239, v240
	s_waitcnt lgkmcnt(3)
	v_mfma_f32_32x32x16_bf16 v[64:79], v[172:175], v[100:103], v[64:79]
	ds_read_b128 v[172:175], v220 offset:0x9010
	v_max3_f32 v226, v226, v241, v242
	v_max_f32_e32 v226, v226, v243
	s_waitcnt lgkmcnt(3)
	v_mfma_f32_32x32x16_bf16 v[48:63], v[160:163], v[80:83], v[48:63]
	ds_read_b128 v[160:163], v221 offset:0x6010
	v_max3_f32 v227, v178, v179, v180
	v_max3_f32 v227, v227, v181, v182
	s_waitcnt lgkmcnt(3)
	v_mfma_f32_32x32x16_bf16 v[32:47], v[164:167], v[80:83], v[32:47]
	ds_read_b128 v[164:167], v221 offset:0x7010
	v_max3_f32 v227, v227, v183, v184
	v_max3_f32 v227, v227, v185, v186
	s_waitcnt lgkmcnt(3)
	v_mfma_f32_32x32x16_bf16 v[16:31], v[168:171], v[80:83], v[16:31]
	ds_read_b128 v[168:171], v221 offset:0x8010
	v_max3_f32 v227, v227, v187, v188
	v_max3_f32 v227, v227, v189, v190
	s_waitcnt lgkmcnt(3)
	v_mfma_f32_32x32x16_bf16 v[64:79], v[172:175], v[80:83], v[64:79]
	ds_read_b128 v[172:175], v221 offset:0x9010
	v_max3_f32 v227, v227, v191, v192
	v_max_f32_e32 v227, v227, v193
	s_waitcnt lgkmcnt(3)
	v_mfma_f32_32x32x16_bf16 v[48:63], v[160:163], v[84:87], v[48:63]
	v_max_f32_e32 v226, v226, v227
	v_mov_b32_e32 v227, v226
	s_waitcnt lgkmcnt(2)
	v_mfma_f32_32x32x16_bf16 v[32:47], v[164:167], v[84:87], v[32:47]
	v_permlane32_swap_b32_e32 v226, v227
	v_max_f32_e32 v226, v226, v227
	s_waitcnt lgkmcnt(1)
	v_mfma_f32_32x32x16_bf16 v[16:31], v[168:171], v[84:87], v[16:31]
	s_waitcnt lgkmcnt(0)
	v_mfma_f32_32x32x16_bf16 v[64:79], v[172:175], v[84:87], v[64:79]
	v_cmp_gt_f32_e32 vcc, v226, v247
	s_cbranch_vccnz .Lp2_rare0
.Lp2_tail0:
	s_add_i32 s19, s19, 1
	s_add_u32 s62, s62, 0x30000
	s_addc_u32 s63, s63, 0
	s_add_u32 s72, s72, 0x80
	s_addc_u32 s73, s73, 0
	s_cmp_eq_u32 s19, s17
	s_cbranch_scc1 .Lp2_exit
.Lp2_top1:
	s_waitcnt vmcnt(0)
	s_barrier
	s_add_i32 s22, s19, 2
	s_add_i32 s24, s19, 1
	s_cmp_gt_i32 s19, s21
	s_cbranch_scc1 .Lp2_idle1
	s_cmp_eq_u32 s19, s21
	s_cbranch_scc1 .Lp2_drain1
	ds_read_b128 v[160:163], v207 offset:0x10
	ds_read_b128 v[164:167], v207 offset:0x3010
	ds_read_b128 v[168:171], v208 offset:0x10
	ds_read_b128 v[172:175], v208 offset:0x3010
	s_waitcnt lgkmcnt(3)
	v_mfma_f32_32x32x16_bf16 v[96:111], v[160:163], v[112:115], v[0:15]
	ds_read_b128 v[160:163], v209 offset:0x10
	v_exp_f32_e32 v228, v228
	v_exp_f32_e32 v229, v229
	s_nop 0
	v_add_f32_e32 v246, v228, v229
	s_waitcnt lgkmcnt(3)
	v_mfma_f32_32x32x16_bf16 v[80:95], v[164:167], v[112:115], v[0:15]
	ds_read_b128 v[164:167], v209 offset:0x3010
	v_cvt_pk_bf16_f32 v228, v228, v229
	v_exp_f32_e32 v230, v230
	v_exp_f32_e32 v231, v231
	s_cmp_ge_i32 s22, s17
	s_cbranch_scc1 .Lp2_nd8
	s_add_i32 m0, s58, 0xa000
	s_nop 0
	global_load_lds_dwordx4 v176, s[62:63]
; __device__ __forceinline__ float fast_exp2(float x) { return __builtin_amdgcn_exp2f(x); }
; __device__ __forceinline__ void attn_phase(int wv, const bf16_t* Q, const bf16_t* Kf, const bf16_t* Vt, const bf16_t* proj, bf16_t* mixed, LAS unsigned char* lds) { LIDS
;     ...
;                     ATT_KRD(0); ATT_KRD(1); ATT_KRD(2); ATT_KRD(3);
; #pragma unroll
;                     for (int i = 0; i < 24; ++i) {
;                         LGK(i < 21 ? 3 : 23 - i, fr_[i & 3]);
;                         s[i & 1] = __builtin_amdgcn_mfma_f32_32x32x16_bf16(fr_[i & 3], qf[i >> 1], s[i & 1], 0, 0, 0);
;                         if (i + 4 < 24) ATT_KRD(i + 4);
;                     }
;     ...
;                     unsigned vad[4];
; #pragma unroll
;                     for (int c = 0; c < 4; ++c) vad[c] = (unsigned)(size_t)vb_ + (unsigned)voffl[c];
;     ...
;                     ATT_VRD(0); ATT_VRD(1); ATT_VRD(2); ATT_VRD(3);
;                     if (64 * t + 63 > qw0) {
; #pragma unroll
;                         for (int kb = 0; kb < 2; ++kb)
; #pragma unroll
;                             for (int j = 0; j < 16; ++j) { const int key = 64 * t + 32 * kb + 16 * (j >> 3) + 8 * h + (j & 7); if (key > q) s[kb][j] = -1e30f; }
;                     }
;                     float mx = -1e30f;
; #pragma unroll
;                     for (int kb = 0; kb < 2; ++kb)
; #pragma unroll
;                         for (int j = 0; j < 16; ++j) mx = fmaxf(mx, s[kb][j]);
;                     mx = fmaxf(mx, __shfl_xor(mx, 32));
;                     if (__builtin_amdgcn_ballot_w64(mx > mrun + 8.0f) != 0ull) {
;                         const float mnew = fmaxf(mrun, mx), alpha = fast_exp2(mrun - mnew); mrun = mnew;
;                         lsum *= alpha;
; #pragma unroll
;                         for (int bb = 0; bb < 4; ++bb)
; #pragma unroll
;                             for (int j = 0; j < 16; ++j) o[bb][j] *= alpha;
;                     }
;                     float ps = 0.f;
; #pragma unroll
;                     for (int kb = 0; kb < 2; ++kb)
; #pragma unroll
;                         for (int j = 0; j < 16; ++j) { s[kb][j] = fast_exp2(s[kb][j] - mrun); ps += s[kb][j]; }
;                     lsum += ps;
; #pragma unroll
;                     for (int c = 0; c < 4; ++c) {
;                         const int kb = c >> 1, sx = c & 1;
;                         u32x4 pw;
; #pragma unroll
.Lp2_nd8:
	s_waitcnt lgkmcnt(3)
	v_mfma_f32_32x32x16_bf16 v[96:111], v[168:171], v[116:119], v[96:111]
	ds_read_b128 v[168:171], v217 offset:0x10
	v_add_f32_e32 v246, v246, v230
	v_add_f32_e32 v246, v246, v231
	v_cvt_pk_bf16_f32 v229, v230, v231
	v_exp_f32_e32 v232, v232
	s_waitcnt lgkmcnt(3)
	v_mfma_f32_32x32x16_bf16 v[80:95], v[172:175], v[116:119], v[80:95]
	ds_read_b128 v[172:175], v217 offset:0x3010
	v_exp_f32_e32 v233, v233
	v_add_f32_e32 v246, v246, v232
	v_add_f32_e32 v246, v246, v233
	v_cvt_pk_bf16_f32 v230, v232, v233
	s_waitcnt lgkmcnt(3)
	v_mfma_f32_32x32x16_bf16 v[96:111], v[160:163], v[120:123], v[96:111]
	ds_read_b128 v[160:163], v207 offset:0x90
	v_exp_f32_e32 v234, v234
	v_exp_f32_e32 v235, v235
	v_add_f32_e32 v246, v246, v234
	s_waitcnt lgkmcnt(3)
	v_mfma_f32_32x32x16_bf16 v[80:95], v[164:167], v[120:123], v[80:95]
	ds_read_b128 v[164:167], v207 offset:0x3090
	v_add_f32_e32 v246, v246, v235
	v_cvt_pk_bf16_f32 v231, v234, v235
	v_exp_f32_e32 v236, v236
	s_cmp_ge_i32 s22, s17
	s_cbranch_scc1 .Lp2_nd9
	s_add_i32 m0, s58, 0xc000
	s_nop 0
	global_load_lds_dwordx4 v194, s[62:63]
.Lp2_nd9:
	s_waitcnt lgkmcnt(3)
	v_mfma_f32_32x32x16_bf16 v[96:111], v[168:171], v[124:127], v[96:111]
	ds_read_b128 v[168:171], v208 offset:0x90
	v_exp_f32_e32 v237, v237
	v_add_f32_e32 v246, v246, v236
	v_add_f32_e32 v246, v246, v237
	v_cvt_pk_bf16_f32 v232, v236, v237
	s_waitcnt lgkmcnt(3)
	v_mfma_f32_32x32x16_bf16 v[80:95], v[172:175], v[124:127], v[80:95]
	ds_read_b128 v[172:175], v208 offset:0x3090
	v_exp_f32_e32 v238, v238
	v_exp_f32_e32 v239, v239
	v_add_f32_e32 v246, v246, v238
	s_waitcnt lgkmcnt(3)
	v_mfma_f32_32x32x16_bf16 v[96:111], v[160:163], v[128:131], v[96:111]
	ds_read_b128 v[160:163], v209 offset:0x90
	v_add_f32_e32 v246, v246, v239
	v_cvt_pk_bf16_f32 v233, v238, v239
	v_exp_f32_e32 v240, v240
	s_waitcnt lgkmcnt(3)
	v_mfma_f32_32x32x16_bf16 v[80:95], v[164:167], v[128:131], v[80:95]
	ds_read_b128 v[164:167], v209 offset:0x3090
	v_exp_f32_e32 v241, v241
	v_add_f32_e32 v246, v246, v240
	v_add_f32_e32 v246, v246, v241
	v_cvt_pk_bf16_f32 v234, v240, v241
	s_cmp_ge_i32 s22, s17
	s_cbranch_scc1 .Lp2_nd10
	s_add_i32 m0, s58, 0xe000
	s_nop 0
	global_load_lds_dwordx4 v196, s[62:63]
.Lp2_nd10:
	s_waitcnt lgkmcnt(3)
	v_mfma_f32_32x32x16_bf16 v[96:111], v[168:171], v[132:135], v[96:111]
	ds_read_b128 v[168:171], v217 offset:0x90
	v_exp_f32_e32 v242, v242
	v_exp_f32_e32 v243, v243
	v_add_f32_e32 v246, v246, v242
	s_waitcnt lgkmcnt(3)
	v_mfma_f32_32x32x16_bf16 v[80:95], v[172:175], v[132:135], v[80:95]
	ds_read_b128 v[172:175], v217 offset:0x3090
	v_add_f32_e32 v246, v246, v243
	v_cvt_pk_bf16_f32 v235, v242, v243
	v_exp_f32_e32 v178, v178
	s_waitcnt lgkmcnt(3)
	v_mfma_f32_32x32x16_bf16 v[96:111], v[160:163], v[136:139], v[96:111]
	ds_read_b128 v[160:163], v207 offset:0x110
	v_exp_f32_e32 v179, v179
	v_add_f32_e32 v246, v246, v178
	v_add_f32_e32 v246, v246, v179
	v_cvt_pk_bf16_f32 v178, v178, v179
	s_waitcnt lgkmcnt(3)
	v_mfma_f32_32x32x16_bf16 v[80:95], v[164:167], v[136:139], v[80:95]
	ds_read_b128 v[164:167], v207 offset:0x3110
	v_exp_f32_e32 v180, v180
	v_exp_f32_e32 v181, v181
	v_add_f32_e32 v246, v246, v180
	s_cmp_ge_i32 s24, s17
	s_cbranch_scc1 .Lp2_nd11
	s_add_i32 m0, s58, 0x6000
	s_nop 0
	global_load_lds_dwordx4 v198, s[72:73]
.Lp2_nd11:
	s_waitcnt lgkmcnt(3)
	v_mfma_f32_32x32x16_bf16 v[96:111], v[168:171], v[140:143], v[96:111]
	ds_read_b128 v[168:171], v208 offset:0x110
	v_add_f32_e32 v246, v246, v181
	v_cvt_pk_bf16_f32 v179, v180, v181
	v_exp_f32_e32 v182, v182
	s_waitcnt lgkmcnt(3)
	v_mfma_f32_32x32x16_bf16 v[80:95], v[172:175], v[140:143], v[80:95]
	ds_read_b128 v[172:175], v208 offset:0x3110
	v_exp_f32_e32 v183, v183
	v_add_f32_e32 v246, v246, v182
	v_add_f32_e32 v246, v246, v183
	v_cvt_pk_bf16_f32 v180, v182, v183
	s_waitcnt lgkmcnt(3)
	v_mfma_f32_32x32x16_bf16 v[96:111], v[160:163], v[144:147], v[96:111]
	ds_read_b128 v[160:163], v209 offset:0x110
	v_exp_f32_e32 v184, v184
	v_exp_f32_e32 v185, v185
	v_add_f32_e32 v246, v246, v184
	s_waitcnt lgkmcnt(3)
	v_mfma_f32_32x32x16_bf16 v[80:95], v[164:167], v[144:147], v[80:95]
	ds_read_b128 v[164:167], v209 offset:0x3110
	v_add_f32_e32 v246, v246, v185
	v_cvt_pk_bf16_f32 v181, v184, v185
	v_exp_f32_e32 v186, v186
	s_cmp_ge_i32 s24, s17
	s_cbranch_scc1 .Lp2_nd12
	s_add_i32 m0, s58, 0x8000
	s_nop 0
	global_load_lds_dwordx4 v200, s[72:73]
; #define LGK(n, f) asm volatile("s_waitcnt lgkmcnt(%1)" : "+v"(f) : "n"(n))
; #define ATT_KRD(i) DSR(fr_[(i) & 3], kad[((i) >> 1) & 3], ((i) & 1) * (32 * 384) + ((i) >> 3) * 128)
; #define ATT_VRD(j) DSR(fr_[(j) & 3], vad[(j) >> 2], ((j) & 3) * 4096)
; __device__ __forceinline__ void attn_phase(int wv, const bf16_t* Q, const bf16_t* Kf, const bf16_t* Vt, const bf16_t* proj, bf16_t* mixed, LAS unsigned char* lds) { LIDS
;     ...
;                     ATT_KRD(0); ATT_KRD(1); ATT_KRD(2); ATT_KRD(3);
; #pragma unroll
;                     for (int i = 0; i < 24; ++i) {
;                         LGK(i < 21 ? 3 : 23 - i, fr_[i & 3]);
;                         s[i & 1] = __builtin_amdgcn_mfma_f32_32x32x16_bf16(fr_[i & 3], qf[i >> 1], s[i & 1], 0, 0, 0);
;                         if (i + 4 < 24) ATT_KRD(i + 4);
;                     }
;     ...
;                     unsigned vad[4];
; #pragma unroll
;                     for (int c = 0; c < 4; ++c) vad[c] = (unsigned)(size_t)vb_ + (unsigned)voffl[c];
;     ...
;                     ATT_VRD(0); ATT_VRD(1); ATT_VRD(2); ATT_VRD(3);
;                     if (64 * t + 63 > qw0) {
; #pragma unroll
;                         for (int kb = 0; kb < 2; ++kb)
; #pragma unroll
;                             for (int j = 0; j < 16; ++j) { const int key = 64 * t + 32 * kb + 16 * (j >> 3) + 8 * h + (j & 7); if (key > q) s[kb][j] = -1e30f; }
;                     }
.Lp2_nd12:
	s_waitcnt lgkmcnt(3)
	v_mfma_f32_32x32x16_bf16 v[96:111], v[168:171], v[148:151], v[96:111]
	ds_read_b128 v[168:171], v217 offset:0x110
	v_exp_f32_e32 v187, v187
	v_add_f32_e32 v246, v246, v186
	v_add_f32_e32 v246, v246, v187
	v_cvt_pk_bf16_f32 v182, v186, v187
	s_waitcnt lgkmcnt(3)
	v_mfma_f32_32x32x16_bf16 v[80:95], v[172:175], v[148:151], v[80:95]
	ds_read_b128 v[172:175], v217 offset:0x3110
	v_exp_f32_e32 v188, v188
	v_exp_f32_e32 v189, v189
	v_add_f32_e32 v246, v246, v188
	s_waitcnt lgkmcnt(3)
	v_mfma_f32_32x32x16_bf16 v[96:111], v[160:163], v[152:155], v[96:111]
	ds_read_b128 v[160:163], v210 offset:0x8010
	v_add_f32_e32 v246, v246, v189
	v_cvt_pk_bf16_f32 v183, v188, v189
	v_exp_f32_e32 v190, v190
	s_waitcnt lgkmcnt(3)
	v_mfma_f32_32x32x16_bf16 v[80:95], v[164:167], v[152:155], v[80:95]
	ds_read_b128 v[164:167], v210 offset:0x9010
	v_exp_f32_e32 v191, v191
	v_add_f32_e32 v246, v246, v190
	v_add_f32_e32 v246, v246, v191
	v_cvt_pk_bf16_f32 v184, v190, v191
	s_waitcnt lgkmcnt(3)
	v_mfma_f32_32x32x16_bf16 v[96:111], v[168:171], v[156:159], v[96:111]
	ds_read_b128 v[168:171], v210 offset:0xa010
	v_exp_f32_e32 v192, v192
	v_exp_f32_e32 v193, v193
	v_add_f32_e32 v246, v246, v192
	s_waitcnt lgkmcnt(3)
	v_mfma_f32_32x32x16_bf16 v[80:95], v[172:175], v[156:159], v[80:95]
	ds_read_b128 v[172:175], v210 offset:0xb010
	v_add_f32_e32 v246, v246, v193
	v_cvt_pk_bf16_f32 v185, v192, v193
	v_add_f32_e32 v224, v224, v246
	s_waitcnt lgkmcnt(3)
	v_mfma_f32_32x32x16_bf16 v[48:63], v[160:163], v[228:231], v[48:63]
	ds_read_b128 v[160:163], v211 offset:0x8010
	s_waitcnt lgkmcnt(3)
	v_mfma_f32_32x32x16_bf16 v[32:47], v[164:167], v[228:231], v[32:47]
	ds_read_b128 v[164:167], v211 offset:0x9010
	s_waitcnt lgkmcnt(3)
	v_mfma_f32_32x32x16_bf16 v[16:31], v[168:171], v[228:231], v[16:31]
	ds_read_b128 v[168:171], v211 offset:0xa010
	s_waitcnt lgkmcnt(3)
	v_mfma_f32_32x32x16_bf16 v[64:79], v[172:175], v[228:231], v[64:79]
	ds_read_b128 v[172:175], v211 offset:0xb010
	s_cmp_lg_u32 s24, s21
	s_cbranch_scc1 .Lp2_nomask13
	s_lshl_b32 s23, s21, 6
	v_add_u32_e32 v244, s23, v222
	v_sub_u32_e32 v244, v223, v244
	v_cmp_le_i32_e32 vcc, 0, v244
	s_nop 1
	v_cndmask_b32_e32 v96, v215, v96, vcc
	v_cmp_le_i32_e32 vcc, 1, v244
	s_nop 1
	v_cndmask_b32_e32 v97, v215, v97, vcc
	v_cmp_le_i32_e32 vcc, 2, v244
	s_nop 1
	v_cndmask_b32_e32 v98, v215, v98, vcc
	v_cmp_le_i32_e32 vcc, 3, v244
	s_nop 1
	v_cndmask_b32_e32 v99, v215, v99, vcc
	v_cmp_le_i32_e32 vcc, 4, v244
	s_nop 1
	v_cndmask_b32_e32 v100, v215, v100, vcc
	v_cmp_le_i32_e32 vcc, 5, v244
	s_nop 1
	v_cndmask_b32_e32 v101, v215, v101, vcc
	v_cmp_le_i32_e32 vcc, 6, v244
	s_nop 1
	v_cndmask_b32_e32 v102, v215, v102, vcc
	v_cmp_le_i32_e32 vcc, 7, v244
	s_nop 1
	v_cndmask_b32_e32 v103, v215, v103, vcc
	v_cmp_le_i32_e32 vcc, 16, v244
	s_nop 1
	v_cndmask_b32_e32 v104, v215, v104, vcc
	v_cmp_le_i32_e32 vcc, 17, v244
	s_nop 1
	v_cndmask_b32_e32 v105, v215, v105, vcc
	v_cmp_le_i32_e32 vcc, 18, v244
	s_nop 1
	v_cndmask_b32_e32 v106, v215, v106, vcc
	v_cmp_le_i32_e32 vcc, 19, v244
	s_nop 1
	v_cndmask_b32_e32 v107, v215, v107, vcc
	v_cmp_le_i32_e32 vcc, 20, v244
	s_nop 1
	v_cndmask_b32_e32 v108, v215, v108, vcc
	v_cmp_le_i32_e32 vcc, 21, v244
	s_nop 1
	v_cndmask_b32_e32 v109, v215, v109, vcc
	v_cmp_le_i32_e32 vcc, 22, v244
	s_nop 1
	v_cndmask_b32_e32 v110, v215, v110, vcc
	v_cmp_le_i32_e32 vcc, 23, v244
	s_nop 1
	v_cndmask_b32_e32 v111, v215, v111, vcc
	v_cmp_le_i32_e32 vcc, 32, v244
	s_nop 1
	v_cndmask_b32_e32 v80, v215, v80, vcc
	v_cmp_le_i32_e32 vcc, 33, v244
	s_nop 1
	v_cndmask_b32_e32 v81, v215, v81, vcc
	v_cmp_le_i32_e32 vcc, 34, v244
	s_nop 1
	v_cndmask_b32_e32 v82, v215, v82, vcc
	v_cmp_le_i32_e32 vcc, 35, v244
	s_nop 1
	v_cndmask_b32_e32 v83, v215, v83, vcc
	v_cmp_le_i32_e32 vcc, 36, v244
	s_nop 1
	v_cndmask_b32_e32 v84, v215, v84, vcc
	v_cmp_le_i32_e32 vcc, 37, v244
	s_nop 1
	v_cndmask_b32_e32 v85, v215, v85, vcc
	v_cmp_le_i32_e32 vcc, 38, v244
	s_nop 1
	v_cndmask_b32_e32 v86, v215, v86, vcc
	v_cmp_le_i32_e32 vcc, 39, v244
	s_nop 1
	v_cndmask_b32_e32 v87, v215, v87, vcc
	v_cmp_le_i32_e32 vcc, 48, v244
	s_nop 1
	v_cndmask_b32_e32 v88, v215, v88, vcc
	v_cmp_le_i32_e32 vcc, 49, v244
	s_nop 1
	v_cndmask_b32_e32 v89, v215, v89, vcc
	v_cmp_le_i32_e32 vcc, 50, v244
	s_nop 1
	v_cndmask_b32_e32 v90, v215, v90, vcc
	v_cmp_le_i32_e32 vcc, 51, v244
	s_nop 1
	v_cndmask_b32_e32 v91, v215, v91, vcc
	v_cmp_le_i32_e32 vcc, 52, v244
	s_nop 1
	v_cndmask_b32_e32 v92, v215, v92, vcc
	v_cmp_le_i32_e32 vcc, 53, v244
	s_nop 1
	v_cndmask_b32_e32 v93, v215, v93, vcc
	v_cmp_le_i32_e32 vcc, 54, v244
	s_nop 1
	v_cndmask_b32_e32 v94, v215, v94, vcc
	v_cmp_le_i32_e32 vcc, 55, v244
	s_nop 1
	v_cndmask_b32_e32 v95, v215, v95, vcc
; __device__ __forceinline__ unsigned cvt_pk_bf16(float lo, float hi) { unsigned r; asm volatile("v_cvt_pk_bf16_f32 %0, %1, %2" : "=v"(r) : "v"(lo), "v"(hi)); return r; }
; __device__ __forceinline__ float fast_exp2(float x) { return __builtin_amdgcn_exp2f(x); }
; #define LGK(n, f) asm volatile("s_waitcnt lgkmcnt(%1)" : "+v"(f) : "n"(n))
; #define ATT_VRD(j) DSR(fr_[(j) & 3], vad[(j) >> 2], ((j) & 3) * 4096)
; __device__ __forceinline__ void attn_phase(int wv, const bf16_t* Q, const bf16_t* Kf, const bf16_t* Vt, const bf16_t* proj, bf16_t* mixed, LAS unsigned char* lds) { LIDS
;     ...
;                     float mx = -1e30f;
; #pragma unroll
;                     for (int kb = 0; kb < 2; ++kb)
; #pragma unroll
;                         for (int j = 0; j < 16; ++j) mx = fmaxf(mx, s[kb][j]);
;                     mx = fmaxf(mx, __shfl_xor(mx, 32));
;                     if (__builtin_amdgcn_ballot_w64(mx > mrun + 8.0f) != 0ull) {
;                         const float mnew = fmaxf(mrun, mx), alpha = fast_exp2(mrun - mnew); mrun = mnew;
;                         lsum *= alpha;
; #pragma unroll
;                         for (int bb = 0; bb < 4; ++bb)
; #pragma unroll
;                             for (int j = 0; j < 16; ++j) o[bb][j] *= alpha;
;                     }
;                     float ps = 0.f;
; #pragma unroll
;                     for (int kb = 0; kb < 2; ++kb)
; #pragma unroll
;                         for (int j = 0; j < 16; ++j) { s[kb][j] = fast_exp2(s[kb][j] - mrun); ps += s[kb][j]; }
;                     lsum += ps;
; #pragma unroll
;                     for (int c = 0; c < 4; ++c) {
;                         const int kb = c >> 1, sx = c & 1;
;                         u32x4 pw;
; #pragma unroll
;                         for (int j = 0; j < 4; ++j) pw[j] = cvt_pk_bf16(s[kb][8 * sx + 2 * j], s[kb][8 * sx + 2 * j + 1]);
;                         const bf16x8 pf = __builtin_bit_cast(bf16x8, pw);
; #pragma unroll
;                         for (int bb = 0; bb < 4; ++bb) {
;                             const int j = c * 4 + bb;
;                             LGK(j < 13 ? 3 : 15 - j, fr_[j & 3]);
;                             o[bb] = __builtin_amdgcn_mfma_f32_32x32x16_bf16(fr_[j & 3], pf, o[bb], 0, 0, 0);
;                             if (j + 4 < 16) ATT_VRD(j + 4);
;                         }
;                     }
.Lp2_nomask13:
	s_waitcnt lgkmcnt(3)
	v_mfma_f32_32x32x16_bf16 v[48:63], v[160:163], v[232:235], v[48:63]
	ds_read_b128 v[160:163], v212 offset:0x8010
	v_max3_f32 v226, v96, v97, v98
	v_max3_f32 v226, v226, v99, v100
	s_waitcnt lgkmcnt(3)
	v_mfma_f32_32x32x16_bf16 v[32:47], v[164:167], v[232:235], v[32:47]
	ds_read_b128 v[164:167], v212 offset:0x9010
	v_max3_f32 v226, v226, v101, v102
	v_max3_f32 v226, v226, v103, v104
	s_waitcnt lgkmcnt(3)
	v_mfma_f32_32x32x16_bf16 v[16:31], v[168:171], v[232:235], v[16:31]
	ds_read_b128 v[168:171], v212 offset:0xa010
	v_max3_f32 v226, v226, v105, v106
	v_max3_f32 v226, v226, v107, v108
	s_waitcnt lgkmcnt(3)
	v_mfma_f32_32x32x16_bf16 v[64:79], v[172:175], v[232:235], v[64:79]
	ds_read_b128 v[172:175], v212 offset:0xb010
	v_max3_f32 v226, v226, v109, v110
	v_max_f32_e32 v226, v226, v111
	s_waitcnt lgkmcnt(3)
	v_mfma_f32_32x32x16_bf16 v[48:63], v[160:163], v[178:181], v[48:63]
	ds_read_b128 v[160:163], v213 offset:0x8010
	v_max3_f32 v227, v80, v81, v82
	v_max3_f32 v227, v227, v83, v84
	s_waitcnt lgkmcnt(3)
	v_mfma_f32_32x32x16_bf16 v[32:47], v[164:167], v[178:181], v[32:47]
	ds_read_b128 v[164:167], v213 offset:0x9010
	v_max3_f32 v227, v227, v85, v86
	v_max3_f32 v227, v227, v87, v88
	s_waitcnt lgkmcnt(3)
	v_mfma_f32_32x32x16_bf16 v[16:31], v[168:171], v[178:181], v[16:31]
	ds_read_b128 v[168:171], v213 offset:0xa010
	v_max3_f32 v227, v227, v89, v90
	v_max3_f32 v227, v227, v91, v92
	s_waitcnt lgkmcnt(3)
	v_mfma_f32_32x32x16_bf16 v[64:79], v[172:175], v[178:181], v[64:79]
	ds_read_b128 v[172:175], v213 offset:0xb010
	v_max3_f32 v227, v227, v93, v94
	v_max_f32_e32 v227, v227, v95
	s_waitcnt lgkmcnt(3)
	v_mfma_f32_32x32x16_bf16 v[48:63], v[160:163], v[182:185], v[48:63]
	v_max_f32_e32 v226, v226, v227
	v_mov_b32_e32 v227, v226
	s_waitcnt lgkmcnt(2)
	v_mfma_f32_32x32x16_bf16 v[32:47], v[164:167], v[182:185], v[32:47]
	v_permlane32_swap_b32_e32 v226, v227
	v_max_f32_e32 v226, v226, v227
	s_waitcnt lgkmcnt(1)
	v_mfma_f32_32x32x16_bf16 v[16:31], v[168:171], v[182:185], v[16:31]
	s_waitcnt lgkmcnt(0)
	v_mfma_f32_32x32x16_bf16 v[64:79], v[172:175], v[182:185], v[64:79]
	v_cmp_gt_f32_e32 vcc, v226, v247
	s_cbranch_vccnz .Lp2_rare1
.Lp2_tail1:
	s_add_i32 s19, s19, 1
	s_add_u32 s62, s62, 0x30000
	s_addc_u32 s63, s63, 0
	s_add_u32 s72, s72, 0x80
	s_addc_u32 s73, s73, 0
	s_cmp_eq_u32 s19, s17
	s_cbranch_scc0 .Lp2_top0
.Lp2_exit:
	s_nop 7
	s_branch .LBB0_96
.Lp2_idle0:
	s_cmp_ge_i32 s22, s17
	s_cbranch_scc1 .Lp2_nd14
	s_mov_b32 m0, s58
	s_nop 0
	global_load_lds_dwordx4 v176, s[62:63]
.Lp2_nd14:
	s_cmp_ge_i32 s22, s17
	s_cbranch_scc1 .Lp2_nd15
	s_add_i32 m0, s58, 0x2000
	s_nop 0
	global_load_lds_dwordx4 v194, s[62:63]
.Lp2_nd15:
	s_cmp_ge_i32 s22, s17
	s_cbranch_scc1 .Lp2_nd16
	s_add_i32 m0, s58, 0x4000
	s_nop 0
	global_load_lds_dwordx4 v196, s[62:63]
.Lp2_nd16:
	s_cmp_ge_i32 s24, s17
	s_cbranch_scc1 .Lp2_nd17
	s_add_i32 m0, s58, 0x10000
	s_nop 0
	global_load_lds_dwordx4 v198, s[72:73]
.Lp2_nd17:
	s_cmp_ge_i32 s24, s17
	s_cbranch_scc1 .Lp2_nd18
	s_add_i32 m0, s58, 0x12000
	s_nop 0
	global_load_lds_dwordx4 v200, s[72:73]

; __device__ __forceinline__ void attn_phase(int wv, const bf16_t* Q, const bf16_t* Kf, const bf16_t* Vt, const bf16_t* proj, bf16_t* mixed, LAS unsigned char* lds) { LIDS
;     ...
;                 if (t + 1 < nt) ATT_ISSUE(t + 1, b ^ 1);
.Lp2_idle1:
	s_cmp_ge_i32 s22, s17
	s_cbranch_scc1 .Lp2_nd19
	s_add_i32 m0, s58, 0xa000
	s_nop 0
	global_load_lds_dwordx4 v176, s[62:63]
.Lp2_nd19:
	s_cmp_ge_i32 s22, s17
	s_cbranch_scc1 .Lp2_nd20
	s_add_i32 m0, s58, 0xc000
	s_nop 0
	global_load_lds_dwordx4 v194, s[62:63]
.Lp2_nd20:
	s_cmp_ge_i32 s22, s17
	s_cbranch_scc1 .Lp2_nd21
	s_add_i32 m0, s58, 0xe000
	s_nop 0
	global_load_lds_dwordx4 v196, s[62:63]
.Lp2_nd21:
	s_cmp_ge_i32 s24, s17
	s_cbranch_scc1 .Lp2_nd22
	s_add_i32 m0, s58, 0x6000
	s_nop 0
	global_load_lds_dwordx4 v198, s[72:73]
.Lp2_nd22:
	s_cmp_ge_i32 s24, s17
	s_cbranch_scc1 .Lp2_nd23
	s_add_i32 m0, s58, 0x8000
	s_nop 0
	global_load_lds_dwordx4 v200, s[72:73]

; #define ATT_VRD(j) DSR(fr_[(j) & 3], vad[(j) >> 2], ((j) & 3) * 4096)
; __device__ __forceinline__ void attn_phase(int wv, const bf16_t* Q, const bf16_t* Kf, const bf16_t* Vt, const bf16_t* proj, bf16_t* mixed, LAS unsigned char* lds) { LIDS
;     ...
;                     unsigned vad[4];
; #pragma unroll
;                     for (int c = 0; c < 4; ++c) vad[c] = (unsigned)(size_t)vb_ + (unsigned)voffl[c];
;     ...
;                     ATT_VRD(0); ATT_VRD(1); ATT_VRD(2); ATT_VRD(3);
.Lp2_drain0:
	ds_read_b128 v[160:163], v218 offset:0x6010
	ds_read_b128 v[164:167], v218 offset:0x7010
	ds_read_b128 v[168:171], v218 offset:0x8010
	ds_read_b128 v[172:175], v218 offset:0x9010
	s_cmp_ge_i32 s22, s17
	s_cbranch_scc1 .Lp2_nd24
	s_mov_b32 m0, s58
	s_nop 0
	global_load_lds_dwordx4 v176, s[62:63]

; __device__ __forceinline__ unsigned cvt_pk_bf16(float lo, float hi) { unsigned r; asm volatile("v_cvt_pk_bf16_f32 %0, %1, %2" : "=v"(r) : "v"(lo), "v"(hi)); return r; }
; __device__ __forceinline__ float fast_exp2(float x) { return __builtin_amdgcn_exp2f(x); }
; #define LGK(n, f) asm volatile("s_waitcnt lgkmcnt(%1)" : "+v"(f) : "n"(n))
; #define ATT_VRD(j) DSR(fr_[(j) & 3], vad[(j) >> 2], ((j) & 3) * 4096)
; __device__ __forceinline__ void attn_phase(int wv, const bf16_t* Q, const bf16_t* Kf, const bf16_t* Vt, const bf16_t* proj, bf16_t* mixed, LAS unsigned char* lds) { LIDS
;     ...
;                     float ps = 0.f;
; #pragma unroll
;                     for (int kb = 0; kb < 2; ++kb)
; #pragma unroll
;                         for (int j = 0; j < 16; ++j) { s[kb][j] = fast_exp2(s[kb][j] - mrun); ps += s[kb][j]; }
;                     lsum += ps;
; #pragma unroll
;                     for (int c = 0; c < 4; ++c) {
;                         const int kb = c >> 1, sx = c & 1;
;                         u32x4 pw;
; #pragma unroll
;                         for (int j = 0; j < 4; ++j) pw[j] = cvt_pk_bf16(s[kb][8 * sx + 2 * j], s[kb][8 * sx + 2 * j + 1]);
;                         const bf16x8 pf = __builtin_bit_cast(bf16x8, pw);
; #pragma unroll
;                         for (int bb = 0; bb < 4; ++bb) {
;                             const int j = c * 4 + bb;
;                             LGK(j < 13 ? 3 : 15 - j, fr_[j & 3]);
;                             o[bb] = __builtin_amdgcn_mfma_f32_32x32x16_bf16(fr_[j & 3], pf, o[bb], 0, 0, 0);
;                             if (j + 4 < 16) ATT_VRD(j + 4);
;                         }
;                     }
.Lp2_nd28:
	v_exp_f32_e32 v96, v96
	v_exp_f32_e32 v97, v97
	s_nop 0
	v_add_f32_e32 v246, v96, v97
	v_cvt_pk_bf16_f32 v96, v96, v97
	v_exp_f32_e32 v98, v98
	v_exp_f32_e32 v99, v99
	v_add_f32_e32 v246, v246, v98
	v_add_f32_e32 v246, v246, v99
	v_cvt_pk_bf16_f32 v97, v98, v99
	v_exp_f32_e32 v100, v100
	v_exp_f32_e32 v101, v101
	v_add_f32_e32 v246, v246, v100
	v_add_f32_e32 v246, v246, v101
	v_cvt_pk_bf16_f32 v98, v100, v101
	v_exp_f32_e32 v102, v102
	v_exp_f32_e32 v103, v103
	v_add_f32_e32 v246, v246, v102
	v_add_f32_e32 v246, v246, v103
	v_cvt_pk_bf16_f32 v99, v102, v103
	s_waitcnt lgkmcnt(3)
	s_nop 0
	v_mfma_f32_32x32x16_bf16 v[48:63], v[160:163], v[96:99], v[48:63]
	ds_read_b128 v[160:163], v219 offset:0x6010
	v_exp_f32_e32 v104, v104
	v_exp_f32_e32 v105, v105
	v_add_f32_e32 v246, v246, v104
	v_add_f32_e32 v246, v246, v105
	v_cvt_pk_bf16_f32 v100, v104, v105
	s_waitcnt lgkmcnt(3)
	v_mfma_f32_32x32x16_bf16 v[32:47], v[164:167], v[96:99], v[32:47]
	ds_read_b128 v[164:167], v219 offset:0x7010
	v_exp_f32_e32 v106, v106
	v_exp_f32_e32 v107, v107
	v_add_f32_e32 v246, v246, v106
	v_add_f32_e32 v246, v246, v107
	v_cvt_pk_bf16_f32 v101, v106, v107
	s_waitcnt lgkmcnt(3)
	v_mfma_f32_32x32x16_bf16 v[16:31], v[168:171], v[96:99], v[16:31]
	ds_read_b128 v[168:171], v219 offset:0x8010
	v_exp_f32_e32 v108, v108
	v_exp_f32_e32 v109, v109
	v_add_f32_e32 v246, v246, v108
	v_add_f32_e32 v246, v246, v109
	v_cvt_pk_bf16_f32 v102, v108, v109
	s_waitcnt lgkmcnt(3)
	v_mfma_f32_32x32x16_bf16 v[64:79], v[172:175], v[96:99], v[64:79]
	ds_read_b128 v[172:175], v219 offset:0x9010
	v_exp_f32_e32 v110, v110
	v_exp_f32_e32 v111, v111
	v_add_f32_e32 v246, v246, v110
	v_add_f32_e32 v246, v246, v111
	v_cvt_pk_bf16_f32 v103, v110, v111
	s_waitcnt lgkmcnt(3)
	s_nop 0
	v_mfma_f32_32x32x16_bf16 v[48:63], v[160:163], v[100:103], v[48:63]
	ds_read_b128 v[160:163], v220 offset:0x6010
	v_exp_f32_e32 v80, v80
	v_exp_f32_e32 v81, v81
	v_add_f32_e32 v246, v246, v80
	v_add_f32_e32 v246, v246, v81
	v_cvt_pk_bf16_f32 v80, v80, v81
	s_waitcnt lgkmcnt(3)
	v_mfma_f32_32x32x16_bf16 v[32:47], v[164:167], v[100:103], v[32:47]
	ds_read_b128 v[164:167], v220 offset:0x7010
	v_exp_f32_e32 v82, v82
	v_exp_f32_e32 v83, v83
	v_add_f32_e32 v246, v246, v82
	v_add_f32_e32 v246, v246, v83
	v_cvt_pk_bf16_f32 v81, v82, v83
	s_waitcnt lgkmcnt(3)
	v_mfma_f32_32x32x16_bf16 v[16:31], v[168:171], v[100:103], v[16:31]
	ds_read_b128 v[168:171], v220 offset:0x8010
	v_exp_f32_e32 v84, v84
	v_exp_f32_e32 v85, v85
	v_add_f32_e32 v246, v246, v84
	v_add_f32_e32 v246, v246, v85
	v_cvt_pk_bf16_f32 v82, v84, v85
	s_waitcnt lgkmcnt(3)
	v_mfma_f32_32x32x16_bf16 v[64:79], v[172:175], v[100:103], v[64:79]
	ds_read_b128 v[172:175], v220 offset:0x9010
	v_exp_f32_e32 v86, v86
	v_exp_f32_e32 v87, v87
	v_add_f32_e32 v246, v246, v86
	v_add_f32_e32 v246, v246, v87
	v_cvt_pk_bf16_f32 v83, v86, v87
	s_waitcnt lgkmcnt(3)
	s_nop 0
	v_mfma_f32_32x32x16_bf16 v[48:63], v[160:163], v[80:83], v[48:63]
	ds_read_b128 v[160:163], v221 offset:0x6010
	v_exp_f32_e32 v88, v88
	v_exp_f32_e32 v89, v89
	v_add_f32_e32 v246, v246, v88
	v_add_f32_e32 v246, v246, v89
	v_cvt_pk_bf16_f32 v84, v88, v89
	s_waitcnt lgkmcnt(3)
	v_mfma_f32_32x32x16_bf16 v[32:47], v[164:167], v[80:83], v[32:47]
	ds_read_b128 v[164:167], v221 offset:0x7010
	v_exp_f32_e32 v90, v90
	v_exp_f32_e32 v91, v91
	v_add_f32_e32 v246, v246, v90
	v_add_f32_e32 v246, v246, v91
	v_cvt_pk_bf16_f32 v85, v90, v91
	s_waitcnt lgkmcnt(3)
	v_mfma_f32_32x32x16_bf16 v[16:31], v[168:171], v[80:83], v[16:31]
	ds_read_b128 v[168:171], v221 offset:0x8010
	v_exp_f32_e32 v92, v92
	v_exp_f32_e32 v93, v93
	v_add_f32_e32 v246, v246, v92
	v_add_f32_e32 v246, v246, v93
	v_cvt_pk_bf16_f32 v86, v92, v93
	s_waitcnt lgkmcnt(3)
	v_mfma_f32_32x32x16_bf16 v[64:79], v[172:175], v[80:83], v[64:79]
	ds_read_b128 v[172:175], v221 offset:0x9010
	v_exp_f32_e32 v94, v94
	v_exp_f32_e32 v95, v95
	v_add_f32_e32 v246, v246, v94
	v_add_f32_e32 v246, v246, v95
	v_cvt_pk_bf16_f32 v87, v94, v95
	s_waitcnt lgkmcnt(3)
	s_nop 0
	v_mfma_f32_32x32x16_bf16 v[48:63], v[160:163], v[84:87], v[48:63]
	v_add_f32_e32 v224, v224, v246
	s_waitcnt lgkmcnt(2)
	v_mfma_f32_32x32x16_bf16 v[32:47], v[164:167], v[84:87], v[32:47]
	s_waitcnt lgkmcnt(1)
	v_mfma_f32_32x32x16_bf16 v[16:31], v[168:171], v[84:87], v[16:31]
	s_waitcnt lgkmcnt(0)
	v_mfma_f32_32x32x16_bf16 v[64:79], v[172:175], v[84:87], v[64:79]
	s_branch .Lp2_tail0
.Lp2_drain1:
	ds_read_b128 v[160:163], v210 offset:0x8010
	ds_read_b128 v[164:167], v210 offset:0x9010
	ds_read_b128 v[168:171], v210 offset:0xa010
	ds_read_b128 v[172:175], v210 offset:0xb010
	s_cmp_ge_i32 s22, s17
	s_cbranch_scc1 .Lp2_nd29
	s_add_i32 m0, s58, 0xa000
	s_nop 0
	global_load_lds_dwordx4 v176, s[62:63]

; __device__ __forceinline__ unsigned cvt_pk_bf16(float lo, float hi) { unsigned r; asm volatile("v_cvt_pk_bf16_f32 %0, %1, %2" : "=v"(r) : "v"(lo), "v"(hi)); return r; }
; __device__ __forceinline__ float fast_exp2(float x) { return __builtin_amdgcn_exp2f(x); }
; #define LGK(n, f) asm volatile("s_waitcnt lgkmcnt(%1)" : "+v"(f) : "n"(n))
; #define ATT_VRD(j) DSR(fr_[(j) & 3], vad[(j) >> 2], ((j) & 3) * 4096)
; __device__ __forceinline__ void attn_phase(int wv, const bf16_t* Q, const bf16_t* Kf, const bf16_t* Vt, const bf16_t* proj, bf16_t* mixed, LAS unsigned char* lds) { LIDS
;     ...
;                     float ps = 0.f;
; #pragma unroll
;                     for (int kb = 0; kb < 2; ++kb)
; #pragma unroll
;                         for (int j = 0; j < 16; ++j) { s[kb][j] = fast_exp2(s[kb][j] - mrun); ps += s[kb][j]; }
;                     lsum += ps;
; #pragma unroll
;                     for (int c = 0; c < 4; ++c) {
;                         const int kb = c >> 1, sx = c & 1;
;                         u32x4 pw;
; #pragma unroll
;                         for (int j = 0; j < 4; ++j) pw[j] = cvt_pk_bf16(s[kb][8 * sx + 2 * j], s[kb][8 * sx + 2 * j + 1]);
;                         const bf16x8 pf = __builtin_bit_cast(bf16x8, pw);
; #pragma unroll
;                         for (int bb = 0; bb < 4; ++bb) {
;                             const int j = c * 4 + bb;
;                             LGK(j < 13 ? 3 : 15 - j, fr_[j & 3]);
;                             o[bb] = __builtin_amdgcn_mfma_f32_32x32x16_bf16(fr_[j & 3], pf, o[bb], 0, 0, 0);
;                             if (j + 4 < 16) ATT_VRD(j + 4);
;                         }
;                     }
.Lp2_nd33:
	v_exp_f32_e32 v228, v228
	v_exp_f32_e32 v229, v229
	s_nop 0
	v_add_f32_e32 v246, v228, v229
	v_cvt_pk_bf16_f32 v228, v228, v229
	v_exp_f32_e32 v230, v230
	v_exp_f32_e32 v231, v231
	v_add_f32_e32 v246, v246, v230
	v_add_f32_e32 v246, v246, v231
	v_cvt_pk_bf16_f32 v229, v230, v231
	v_exp_f32_e32 v232, v232
	v_exp_f32_e32 v233, v233
	v_add_f32_e32 v246, v246, v232
	v_add_f32_e32 v246, v246, v233
	v_cvt_pk_bf16_f32 v230, v232, v233
	v_exp_f32_e32 v234, v234
	v_exp_f32_e32 v235, v235
	v_add_f32_e32 v246, v246, v234
	v_add_f32_e32 v246, v246, v235
	v_cvt_pk_bf16_f32 v231, v234, v235
	s_waitcnt lgkmcnt(3)
	s_nop 0
	v_mfma_f32_32x32x16_bf16 v[48:63], v[160:163], v[228:231], v[48:63]
	ds_read_b128 v[160:163], v211 offset:0x8010
	v_exp_f32_e32 v236, v236
	v_exp_f32_e32 v237, v237
	v_add_f32_e32 v246, v246, v236
	v_add_f32_e32 v246, v246, v237
	v_cvt_pk_bf16_f32 v232, v236, v237
	s_waitcnt lgkmcnt(3)
	v_mfma_f32_32x32x16_bf16 v[32:47], v[164:167], v[228:231], v[32:47]
	ds_read_b128 v[164:167], v211 offset:0x9010
	v_exp_f32_e32 v238, v238
	v_exp_f32_e32 v239, v239
	v_add_f32_e32 v246, v246, v238
	v_add_f32_e32 v246, v246, v239
	v_cvt_pk_bf16_f32 v233, v238, v239
	s_waitcnt lgkmcnt(3)
	v_mfma_f32_32x32x16_bf16 v[16:31], v[168:171], v[228:231], v[16:31]
	ds_read_b128 v[168:171], v211 offset:0xa010
	v_exp_f32_e32 v240, v240
	v_exp_f32_e32 v241, v241
	v_add_f32_e32 v246, v246, v240
	v_add_f32_e32 v246, v246, v241
	v_cvt_pk_bf16_f32 v234, v240, v241
	s_waitcnt lgkmcnt(3)
	v_mfma_f32_32x32x16_bf16 v[64:79], v[172:175], v[228:231], v[64:79]
	ds_read_b128 v[172:175], v211 offset:0xb010
	v_exp_f32_e32 v242, v242
	v_exp_f32_e32 v243, v243
	v_add_f32_e32 v246, v246, v242
	v_add_f32_e32 v246, v246, v243
	v_cvt_pk_bf16_f32 v235, v242, v243
	s_waitcnt lgkmcnt(3)
	s_nop 0
	v_mfma_f32_32x32x16_bf16 v[48:63], v[160:163], v[232:235], v[48:63]
	ds_read_b128 v[160:163], v212 offset:0x8010
	v_exp_f32_e32 v178, v178
	v_exp_f32_e32 v179, v179
	v_add_f32_e32 v246, v246, v178
	v_add_f32_e32 v246, v246, v179
	v_cvt_pk_bf16_f32 v178, v178, v179
	s_waitcnt lgkmcnt(3)
	v_mfma_f32_32x32x16_bf16 v[32:47], v[164:167], v[232:235], v[32:47]
	ds_read_b128 v[164:167], v212 offset:0x9010
	v_exp_f32_e32 v180, v180
	v_exp_f32_e32 v181, v181
	v_add_f32_e32 v246, v246, v180
	v_add_f32_e32 v246, v246, v181
	v_cvt_pk_bf16_f32 v179, v180, v181
	s_waitcnt lgkmcnt(3)
	v_mfma_f32_32x32x16_bf16 v[16:31], v[168:171], v[232:235], v[16:31]
	ds_read_b128 v[168:171], v212 offset:0xa010
	v_exp_f32_e32 v182, v182
	v_exp_f32_e32 v183, v183
	v_add_f32_e32 v246, v246, v182
	v_add_f32_e32 v246, v246, v183
	v_cvt_pk_bf16_f32 v180, v182, v183
	s_waitcnt lgkmcnt(3)
	v_mfma_f32_32x32x16_bf16 v[64:79], v[172:175], v[232:235], v[64:79]
	ds_read_b128 v[172:175], v212 offset:0xb010
	v_exp_f32_e32 v184, v184
	v_exp_f32_e32 v185, v185
	v_add_f32_e32 v246, v246, v184
	v_add_f32_e32 v246, v246, v185
	v_cvt_pk_bf16_f32 v181, v184, v185
	s_waitcnt lgkmcnt(3)
	s_nop 0
	v_mfma_f32_32x32x16_bf16 v[48:63], v[160:163], v[178:181], v[48:63]
	ds_read_b128 v[160:163], v213 offset:0x8010
	v_exp_f32_e32 v186, v186
	v_exp_f32_e32 v187, v187
	v_add_f32_e32 v246, v246, v186
	v_add_f32_e32 v246, v246, v187
	v_cvt_pk_bf16_f32 v182, v186, v187
	s_waitcnt lgkmcnt(3)
	v_mfma_f32_32x32x16_bf16 v[32:47], v[164:167], v[178:181], v[32:47]
	ds_read_b128 v[164:167], v213 offset:0x9010
	v_exp_f32_e32 v188, v188
	v_exp_f32_e32 v189, v189
	v_add_f32_e32 v246, v246, v188
	v_add_f32_e32 v246, v246, v189
	v_cvt_pk_bf16_f32 v183, v188, v189
	s_waitcnt lgkmcnt(3)
	v_mfma_f32_32x32x16_bf16 v[16:31], v[168:171], v[178:181], v[16:31]
	ds_read_b128 v[168:171], v213 offset:0xa010
	v_exp_f32_e32 v190, v190
	v_exp_f32_e32 v191, v191
	v_add_f32_e32 v246, v246, v190
	v_add_f32_e32 v246, v246, v191
	v_cvt_pk_bf16_f32 v184, v190, v191
	s_waitcnt lgkmcnt(3)
	v_mfma_f32_32x32x16_bf16 v[64:79], v[172:175], v[178:181], v[64:79]
	ds_read_b128 v[172:175], v213 offset:0xb010
	v_exp_f32_e32 v192, v192
	v_exp_f32_e32 v193, v193
	v_add_f32_e32 v246, v246, v192
	v_add_f32_e32 v246, v246, v193
	v_cvt_pk_bf16_f32 v185, v192, v193
	s_waitcnt lgkmcnt(3)
	s_nop 0
	v_mfma_f32_32x32x16_bf16 v[48:63], v[160:163], v[182:185], v[48:63]
	v_add_f32_e32 v224, v224, v246
	s_waitcnt lgkmcnt(2)
	v_mfma_f32_32x32x16_bf16 v[32:47], v[164:167], v[182:185], v[32:47]
	s_waitcnt lgkmcnt(1)
	v_mfma_f32_32x32x16_bf16 v[16:31], v[168:171], v[182:185], v[16:31]
	s_waitcnt lgkmcnt(0)
	v_mfma_f32_32x32x16_bf16 v[64:79], v[172:175], v[182:185], v[64:79]
	s_branch .Lp2_tail1
; __device__ __forceinline__ float fast_exp2(float x) { return __builtin_amdgcn_exp2f(x); }
; __device__ __forceinline__ void attn_phase(int wv, const bf16_t* Q, const bf16_t* Kf, const bf16_t* Vt, const bf16_t* proj, bf16_t* mixed, LAS unsigned char* lds) { LIDS
;     ...
;                     if (__builtin_amdgcn_ballot_w64(mx > mrun + 8.0f) != 0ull) {
;                         const float mnew = fmaxf(mrun, mx), alpha = fast_exp2(mrun - mnew); mrun = mnew;
;                         lsum *= alpha;
; #pragma unroll
;                         for (int bb = 0; bb < 4; ++bb)
; #pragma unroll
;                             for (int j = 0; j < 16; ++j) o[bb][j] *= alpha;
;                     }
.Lp2_rare0:
	s_nop 15
	v_sub_f32_e32 v244, v226, v0
	v_max_f32_e32 v227, v225, v244
	v_sub_f32_e32 v244, v225, v227
	v_exp_f32_e32 v244, v244
	v_add_f32_e32 v245, v227, v0
	v_mov_b32_e32 v225, v227
	v_mov_b32_e32 v247, 0x41000000
	v_sub_f32_e32 v228, v228, v245
	v_sub_f32_e32 v229, v229, v245
	v_sub_f32_e32 v230, v230, v245
	v_sub_f32_e32 v231, v231, v245
	v_sub_f32_e32 v232, v232, v245
	v_sub_f32_e32 v233, v233, v245
	v_sub_f32_e32 v234, v234, v245
	v_sub_f32_e32 v235, v235, v245
	v_sub_f32_e32 v236, v236, v245
	v_sub_f32_e32 v237, v237, v245
	v_sub_f32_e32 v238, v238, v245
	v_sub_f32_e32 v239, v239, v245
	v_sub_f32_e32 v240, v240, v245
	v_sub_f32_e32 v241, v241, v245
	v_sub_f32_e32 v242, v242, v245
	v_sub_f32_e32 v243, v243, v245
	v_sub_f32_e32 v178, v178, v245
	v_sub_f32_e32 v179, v179, v245
	v_sub_f32_e32 v180, v180, v245
	v_sub_f32_e32 v181, v181, v245
	v_sub_f32_e32 v182, v182, v245
	v_sub_f32_e32 v183, v183, v245
	v_sub_f32_e32 v184, v184, v245
	v_sub_f32_e32 v185, v185, v245
	v_sub_f32_e32 v186, v186, v245
	v_sub_f32_e32 v187, v187, v245
	v_sub_f32_e32 v188, v188, v245
	v_sub_f32_e32 v189, v189, v245
	v_sub_f32_e32 v190, v190, v245
	v_sub_f32_e32 v191, v191, v245
	v_sub_f32_e32 v192, v192, v245
	v_sub_f32_e32 v193, v193, v245
	v_sub_f32_e32 v0, 0, v227
	v_mov_b32_e32 v1, v0
	v_mov_b32_e32 v2, v0
	v_mov_b32_e32 v3, v0
	v_mov_b32_e32 v4, v0
	v_mov_b32_e32 v5, v0
	v_mov_b32_e32 v6, v0
	v_mov_b32_e32 v7, v0
	v_mov_b32_e32 v8, v0
	v_mov_b32_e32 v9, v0
	v_mov_b32_e32 v10, v0
	v_mov_b32_e32 v11, v0
	v_mov_b32_e32 v12, v0
	v_mov_b32_e32 v13, v0
	v_mov_b32_e32 v14, v0
	v_mov_b32_e32 v15, v0
	v_mul_f32_e32 v48, v244, v48
	v_mul_f32_e32 v49, v244, v49
	v_mul_f32_e32 v50, v244, v50
	v_mul_f32_e32 v51, v244, v51
	v_mul_f32_e32 v52, v244, v52
	v_mul_f32_e32 v53, v244, v53
	v_mul_f32_e32 v54, v244, v54
	v_mul_f32_e32 v55, v244, v55
	v_mul_f32_e32 v56, v244, v56
	v_mul_f32_e32 v57, v244, v57
	v_mul_f32_e32 v58, v244, v58
	v_mul_f32_e32 v59, v244, v59
	v_mul_f32_e32 v60, v244, v60
	v_mul_f32_e32 v61, v244, v61
	v_mul_f32_e32 v62, v244, v62
	v_mul_f32_e32 v63, v244, v63
	v_mul_f32_e32 v32, v244, v32
	v_mul_f32_e32 v33, v244, v33
	v_mul_f32_e32 v34, v244, v34
	v_mul_f32_e32 v35, v244, v35
	v_mul_f32_e32 v36, v244, v36
	v_mul_f32_e32 v37, v244, v37
	v_mul_f32_e32 v38, v244, v38
	v_mul_f32_e32 v39, v244, v39
	v_mul_f32_e32 v40, v244, v40
	v_mul_f32_e32 v41, v244, v41
	v_mul_f32_e32 v42, v244, v42
	v_mul_f32_e32 v43, v244, v43
	v_mul_f32_e32 v44, v244, v44
	v_mul_f32_e32 v45, v244, v45
	v_mul_f32_e32 v46, v244, v46
	v_mul_f32_e32 v47, v244, v47
	v_mul_f32_e32 v16, v244, v16
	v_mul_f32_e32 v17, v244, v17
	v_mul_f32_e32 v18, v244, v18
	v_mul_f32_e32 v19, v244, v19
	v_mul_f32_e32 v20, v244, v20
	v_mul_f32_e32 v21, v244, v21
	v_mul_f32_e32 v22, v244, v22
	v_mul_f32_e32 v23, v244, v23
	v_mul_f32_e32 v24, v244, v24
	v_mul_f32_e32 v25, v244, v25
	v_mul_f32_e32 v26, v244, v26
	v_mul_f32_e32 v27, v244, v27
	v_mul_f32_e32 v28, v244, v28
	v_mul_f32_e32 v29, v244, v29
	v_mul_f32_e32 v30, v244, v30
	v_mul_f32_e32 v31, v244, v31
	v_mul_f32_e32 v64, v244, v64
	v_mul_f32_e32 v65, v244, v65
	v_mul_f32_e32 v66, v244, v66
	v_mul_f32_e32 v67, v244, v67
	v_mul_f32_e32 v68, v244, v68
	v_mul_f32_e32 v69, v244, v69
	v_mul_f32_e32 v70, v244, v70
	v_mul_f32_e32 v71, v244, v71
	v_mul_f32_e32 v72, v244, v72
	v_mul_f32_e32 v73, v244, v73
	v_mul_f32_e32 v74, v244, v74
	v_mul_f32_e32 v75, v244, v75
	v_mul_f32_e32 v76, v244, v76
	v_mul_f32_e32 v77, v244, v77
	v_mul_f32_e32 v78, v244, v78
	v_mul_f32_e32 v79, v244, v79
	v_mul_f32_e32 v224, v244, v224
	s_branch .Lp2_tail0
; __device__ __forceinline__ float fast_exp2(float x) { return __builtin_amdgcn_exp2f(x); }
; __device__ __forceinline__ void attn_phase(int wv, const bf16_t* Q, const bf16_t* Kf, const bf16_t* Vt, const bf16_t* proj, bf16_t* mixed, LAS unsigned char* lds) { LIDS
;     ...
;                     if (__builtin_amdgcn_ballot_w64(mx > mrun + 8.0f) != 0ull) {
;                         const float mnew = fmaxf(mrun, mx), alpha = fast_exp2(mrun - mnew); mrun = mnew;
;                         lsum *= alpha;
; #pragma unroll
;                         for (int bb = 0; bb < 4; ++bb)
; #pragma unroll
;                             for (int j = 0; j < 16; ++j) o[bb][j] *= alpha;
;                     }
.Lp2_rare1:
	s_nop 15
	v_sub_f32_e32 v244, v226, v0
	v_max_f32_e32 v227, v225, v244
	v_sub_f32_e32 v244, v225, v227
	v_exp_f32_e32 v244, v244
	v_add_f32_e32 v245, v227, v0
	v_mov_b32_e32 v225, v227
	v_mov_b32_e32 v247, 0x41000000
	v_sub_f32_e32 v96, v96, v245
	v_sub_f32_e32 v97, v97, v245
	v_sub_f32_e32 v98, v98, v245
	v_sub_f32_e32 v99, v99, v245
	v_sub_f32_e32 v100, v100, v245
	v_sub_f32_e32 v101, v101, v245
	v_sub_f32_e32 v102, v102, v245
	v_sub_f32_e32 v103, v103, v245
	v_sub_f32_e32 v104, v104, v245
	v_sub_f32_e32 v105, v105, v245
	v_sub_f32_e32 v106, v106, v245
	v_sub_f32_e32 v107, v107, v245
	v_sub_f32_e32 v108, v108, v245
	v_sub_f32_e32 v109, v109, v245
	v_sub_f32_e32 v110, v110, v245
	v_sub_f32_e32 v111, v111, v245
	v_sub_f32_e32 v80, v80, v245
	v_sub_f32_e32 v81, v81, v245
	v_sub_f32_e32 v82, v82, v245
	v_sub_f32_e32 v83, v83, v245
	v_sub_f32_e32 v84, v84, v245
	v_sub_f32_e32 v85, v85, v245
	v_sub_f32_e32 v86, v86, v245
	v_sub_f32_e32 v87, v87, v245
	v_sub_f32_e32 v88, v88, v245
	v_sub_f32_e32 v89, v89, v245
	v_sub_f32_e32 v90, v90, v245
	v_sub_f32_e32 v91, v91, v245
	v_sub_f32_e32 v92, v92, v245
	v_sub_f32_e32 v93, v93, v245
	v_sub_f32_e32 v94, v94, v245
	v_sub_f32_e32 v95, v95, v245
	v_sub_f32_e32 v0, 0, v227
	v_mov_b32_e32 v1, v0
	v_mov_b32_e32 v2, v0
	v_mov_b32_e32 v3, v0
	v_mov_b32_e32 v4, v0
	v_mov_b32_e32 v5, v0
	v_mov_b32_e32 v6, v0
	v_mov_b32_e32 v7, v0
	v_mov_b32_e32 v8, v0
	v_mov_b32_e32 v9, v0
	v_mov_b32_e32 v10, v0
	v_mov_b32_e32 v11, v0
	v_mov_b32_e32 v12, v0
	v_mov_b32_e32 v13, v0
	v_mov_b32_e32 v14, v0
	v_mov_b32_e32 v15, v0
	v_mul_f32_e32 v48, v244, v48
	v_mul_f32_e32 v49, v244, v49
	v_mul_f32_e32 v50, v244, v50
	v_mul_f32_e32 v51, v244, v51
	v_mul_f32_e32 v52, v244, v52
	v_mul_f32_e32 v53, v244, v53
	v_mul_f32_e32 v54, v244, v54
	v_mul_f32_e32 v55, v244, v55
	v_mul_f32_e32 v56, v244, v56
	v_mul_f32_e32 v57, v244, v57
	v_mul_f32_e32 v58, v244, v58
	v_mul_f32_e32 v59, v244, v59
	v_mul_f32_e32 v60, v244, v60
	v_mul_f32_e32 v61, v244, v61
	v_mul_f32_e32 v62, v244, v62
	v_mul_f32_e32 v63, v244, v63
	v_mul_f32_e32 v32, v244, v32
	v_mul_f32_e32 v33, v244, v33
	v_mul_f32_e32 v34, v244, v34
	v_mul_f32_e32 v35, v244, v35
	v_mul_f32_e32 v36, v244, v36
	v_mul_f32_e32 v37, v244, v37
	v_mul_f32_e32 v38, v244, v38
	v_mul_f32_e32 v39, v244, v39
	v_mul_f32_e32 v40, v244, v40
	v_mul_f32_e32 v41, v244, v41
	v_mul_f32_e32 v42, v244, v42
	v_mul_f32_e32 v43, v244, v43
	v_mul_f32_e32 v44, v244, v44
	v_mul_f32_e32 v45, v244, v45
	v_mul_f32_e32 v46, v244, v46
	v_mul_f32_e32 v47, v244, v47
	v_mul_f32_e32 v16, v244, v16
	v_mul_f32_e32 v17, v244, v17
	v_mul_f32_e32 v18, v244, v18
	v_mul_f32_e32 v19, v244, v19
	v_mul_f32_e32 v20, v244, v20
	v_mul_f32_e32 v21, v244, v21
	v_mul_f32_e32 v22, v244, v22
	v_mul_f32_e32 v23, v244, v23
	v_mul_f32_e32 v24, v244, v24
	v_mul_f32_e32 v25, v244, v25
	v_mul_f32_e32 v26, v244, v26
	v_mul_f32_e32 v27, v244, v27
	v_mul_f32_e32 v28, v244, v28
	v_mul_f32_e32 v29, v244, v29
	v_mul_f32_e32 v30, v244, v30
	v_mul_f32_e32 v31, v244, v31
	v_mul_f32_e32 v64, v244, v64
	v_mul_f32_e32 v65, v244, v65
	v_mul_f32_e32 v66, v244, v66
	v_mul_f32_e32 v67, v244, v67
	v_mul_f32_e32 v68, v244, v68
	v_mul_f32_e32 v69, v244, v69
	v_mul_f32_e32 v70, v244, v70
	v_mul_f32_e32 v71, v244, v71
	v_mul_f32_e32 v72, v244, v72
	v_mul_f32_e32 v73, v244, v73
	v_mul_f32_e32 v74, v244, v74
	v_mul_f32_e32 v75, v244, v75
	v_mul_f32_e32 v76, v244, v76
	v_mul_f32_e32 v77, v244, v77
	v_mul_f32_e32 v78, v244, v78
	v_mul_f32_e32 v79, v244, v79
	v_mul_f32_e32 v224, v244, v224
	s_branch .Lp2_tail1

; __device__ __forceinline__ void attn_phase(int wv, const bf16_t* Q, const bf16_t* Kf, const bf16_t* Vt, const bf16_t* proj, bf16_t* mixed, LAS unsigned char* lds) { LIDS
;     ...
;     __builtin_amdgcn_s_setprio(0);
;     asm volatile("s_waitcnt vmcnt(0)" ::: "memory"); __builtin_amdgcn_s_barrier(); asm volatile("" ::: "memory");
.LBB0_110:
	v_readlane_b32 s26, v254, 50
	v_readlane_b32 s27, v254, 51
	v_readlane_b32 s23, v254, 53
	v_readlane_b32 s58, v254, 54
	v_readlane_b32 s59, v254, 55
	v_mov_b32_e32 v217, 1
